# stack9 + lagging half's offset barrier moved behind the next-unit scalar block (before zeroing / peeled load segment), 14 GEMM instances
# speedup vs baseline: 1.0004x; 1.0004x over previous
; #define PG8_STAGE(bufoff, gbase, voff) do { _Pragma("unroll") for (int _i = 0; _i < 2; ++_i) \
;         __builtin_amdgcn_global_load_lds((const unsigned*)((const char*)(gbase) + (voff)[_i]), (PG8_LAS unsigned*)(lds + (bufoff) + ldsw + _i * 8192), 16, 0, 0); } while (0)
; #define PG8_LDA(dst, b, h) do { _Pragma("unroll") for (int m = 0; m < 4; ++m) _Pragma("unroll") for (int k = 0; k < 2; ++k) dst[m][k] = *(const PG8_LAS bf16x8*)(lds + PG8_SA(b, h) + aoff + m * 2048 + k * 1024); } while (0)
; #define PG8_LDB(dst, b, h) do { _Pragma("unroll") for (int n = 0; n < 2; ++n) _Pragma("unroll") for (int k = 0; k < 2; ++k) dst[n][k] = *(const PG8_LAS bf16x8*)(lds + PG8_SB(b, h) + boff + n * 2048 + k * 1024); } while (0)
; #define PG8_BAR __builtin_amdgcn_s_barrier()
; #define PG8_SCHED __builtin_amdgcn_sched_barrier(0)
; template <class Epi, class Sched, bool ALIGN_EPI = false, bool SP2 = false, bool ABLK = false, bool BBLK = false>
; __device__ __forceinline__ void gemm_phase(PG8_LAS unsigned char* lds, const Gemm g, const Sched& S, const Epi& E) {
;     ...
;         const bool has_next = S.next(ui + 1, nxt);
;         const char* nA = has_next ? (const char*)g.A + (size_t)nxt.pm * tstepA : cA; const char* nB = has_next ? (const char*)g.Bt + (size_t)nxt.pn * tstepB : cB;
;         for (int t = 0; t < nt; t += 2) {
;             const bool last = (t == nt - 2);
;             const char* a1 = cA + (size_t)(t + 1) * kstepA;
;             const char* a2 = last ? nA : cA + (size_t)(t + 2) * kstepA; const char* b2 = last ? nB : cB + (size_t)(t + 2) * kstepB;
;             const char* a3 = a2 + kstepA; const char* b3 = b2 + kstepB;
;             if (last && has_next) S.a_ready(nxt);
;             if constexpr (SP2) {
;             PG8_LDB(B0, 0, 0); PG8_LDB(B1, 0, 1); PG8_SCHED; PG8_LDA(At, 0, 0); PG8_STAGE(PG8_SA(1, 1), a1 + hstepA, voffA);
;     ...
; #pragma unroll
;         for (int a = 0; a < 2; ++a)
; #pragma unroll
;             for (int b = 0; b < 2; ++b)
; #pragma unroll
;                 for (int m = 0; m < 4; ++m)
; #pragma unroll
;                     for (int n = 0; n < 2; ++n) acc[a][b][m][n] = (f32x4){0.f, 0.f, 0.f, 0.f};
;         cur = nxt; cA = nA; cB = nB; ++ui;
;         if constexpr (ALIGN_EPI) { if (wr == 1) PG8_BAR; }
.LBB0_215:
	s_ashr_i32 s15, s14, 31
	s_lshl_b64 s[18:19], s[14:15], 20
	s_add_u32 s18, s35, s18
	s_addc_u32 s19, s36, s19
	s_and_b64 s[20:21], s[4:5], exec
	s_cselect_b32 s15, s19, s23
	s_cselect_b32 s65, s18, s22
	s_ashr_i32 s13, s12, 31
	s_lshl_b64 s[20:21], s[12:13], 20
	s_add_u32 s20, s37, s20
	s_addc_u32 s21, s40, s21
	s_and_b64 s[26:27], s[4:5], exec
	s_cselect_b32 s13, s21, s25
	s_cselect_b32 s68, s20, s24
	s_add_u32 s22, s22, 0xc000
	s_addc_u32 s23, s23, 0
	s_add_u32 s72, s24, 0x10000
	v_mov_b32_e32 v2, 0
	s_addc_u32 s73, s25, 0
	s_mov_b32 s81, -2
	s_and_b64 vcc, exec, s[10:11]
	s_cbranch_vccnz .Lrb_f1a
	s_barrier
.Lrb_f1a:
	s_add_u32 s24, s22, 0x4000
	s_addc_u32 s25, s23, 0
	s_cmp_eq_u32 s81, 28
	s_cselect_b32 s28, s65, s24
	s_cselect_b32 s29, s15, s25
	s_cselect_b32 s26, s68, s72
	s_cselect_b32 s27, s13, s73
	s_add_u32 s24, s28, 0x8000
	s_addc_u32 s25, s29, 0
	s_add_i32 s75, 0, 0x10000
	v_add_u32_e32 v142, s75, v145
	s_add_i32 s80, 0, 0x14000
	ds_read_b128 v[148:151], v142
	v_pk_mov_b32 v[2:3], 0, 0
	v_pk_mov_b32 v[4:5], 0, 0
	v_pk_mov_b32 v[6:7], 0, 0
	v_pk_mov_b32 v[8:9], 0, 0
	ds_read_b128 v[152:155], v142 offset:1024
	v_pk_mov_b32 v[10:11], 0, 0
	v_pk_mov_b32 v[12:13], 0, 0
	v_pk_mov_b32 v[14:15], 0, 0
	v_pk_mov_b32 v[16:17], 0, 0
	ds_read_b128 v[156:159], v142 offset:2048
	v_pk_mov_b32 v[18:19], 0, 0
	v_pk_mov_b32 v[20:21], 0, 0
	v_pk_mov_b32 v[22:23], 0, 0
	v_pk_mov_b32 v[24:25], 0, 0
	ds_read_b128 v[160:163], v142 offset:3072
	v_pk_mov_b32 v[26:27], 0, 0
	v_pk_mov_b32 v[28:29], 0, 0
	v_pk_mov_b32 v[30:31], 0, 0
	v_pk_mov_b32 v[32:33], 0, 0
	v_add_u32_e32 v142, s80, v145
	ds_read_b128 v[164:167], v142
	v_pk_mov_b32 v[34:35], 0, 0
	v_pk_mov_b32 v[36:37], 0, 0
	v_pk_mov_b32 v[38:39], 0, 0
	v_pk_mov_b32 v[40:41], 0, 0
	ds_read_b128 v[168:171], v142 offset:1024
	v_pk_mov_b32 v[42:43], 0, 0
	v_pk_mov_b32 v[44:45], 0, 0
	v_pk_mov_b32 v[46:47], 0, 0
	v_pk_mov_b32 v[48:49], 0, 0
	ds_read_b128 v[172:175], v142 offset:2048
	v_pk_mov_b32 v[50:51], 0, 0
	v_pk_mov_b32 v[52:53], 0, 0
	v_pk_mov_b32 v[54:55], 0, 0
	v_pk_mov_b32 v[56:57], 0, 0
	ds_read_b128 v[176:179], v142 offset:3072
	v_pk_mov_b32 v[58:59], 0, 0
	v_pk_mov_b32 v[60:61], 0, 0
	v_pk_mov_b32 v[62:63], 0, 0
	v_pk_mov_b32 v[64:65], 0, 0
	v_lshl_add_u64 v[142:143], s[22:23], 0, v[138:139]
	s_add_i32 m0, s43, 0xc000
	ds_read_b128 v[180:183], v146
	v_pk_mov_b32 v[66:67], 0, 0
	v_pk_mov_b32 v[68:69], 0, 0
	v_pk_mov_b32 v[70:71], 0, 0
	v_pk_mov_b32 v[72:73], 0, 0
	ds_read_b128 v[196:199], v146 offset:1024
	v_pk_mov_b32 v[74:75], 0, 0
	v_pk_mov_b32 v[76:77], 0, 0
	v_pk_mov_b32 v[78:79], 0, 0
	v_pk_mov_b32 v[80:81], 0, 0
	ds_read_b128 v[200:203], v146 offset:2048
	v_pk_mov_b32 v[82:83], 0, 0
	v_pk_mov_b32 v[84:85], 0, 0
	v_pk_mov_b32 v[86:87], 0, 0
	v_pk_mov_b32 v[88:89], 0, 0
	ds_read_b128 v[204:207], v146 offset:3072
	v_pk_mov_b32 v[90:91], 0, 0
	v_pk_mov_b32 v[92:93], 0, 0
	v_pk_mov_b32 v[94:95], 0, 0
	v_pk_mov_b32 v[96:97], 0, 0
	ds_read_b128 v[208:211], v146 offset:4096
	v_pk_mov_b32 v[98:99], 0, 0
	v_pk_mov_b32 v[100:101], 0, 0
	v_pk_mov_b32 v[102:103], 0, 0
	v_pk_mov_b32 v[104:105], 0, 0
	ds_read_b128 v[212:215], v146 offset:5120
	v_pk_mov_b32 v[106:107], 0, 0
	v_pk_mov_b32 v[108:109], 0, 0
	v_pk_mov_b32 v[110:111], 0, 0
	v_pk_mov_b32 v[112:113], 0, 0
	ds_read_b128 v[216:219], v146 offset:6144
	v_pk_mov_b32 v[114:115], 0, 0
	v_pk_mov_b32 v[116:117], 0, 0
	v_pk_mov_b32 v[118:119], 0, 0
	v_pk_mov_b32 v[120:121], 0, 0
	ds_read_b128 v[220:223], v146 offset:7168
	v_pk_mov_b32 v[122:123], 0, 0
	v_pk_mov_b32 v[124:125], 0, 0
	v_pk_mov_b32 v[126:127], 0, 0
	v_pk_mov_b32 v[128:129], 0, 0
	global_load_lds_dwordx4 v[142:143], off
	v_lshl_add_u64 v[142:143], s[22:23], 0, v[140:141]
	s_add_i32 m0, s43, 0xe000
	s_nop 0
	global_load_lds_dwordx4 v[142:143], off
	s_waitcnt vmcnt(8)
	s_waitcnt lgkmcnt(0)
	s_barrier
	s_branch .Lpeel_216

; #define PG8_STAGE(bufoff, gbase, voff) do { _Pragma("unroll") for (int _i = 0; _i < 2; ++_i) \
;         __builtin_amdgcn_global_load_lds((const unsigned*)((const char*)(gbase) + (voff)[_i]), (PG8_LAS unsigned*)(lds + (bufoff) + ldsw + _i * 8192), 16, 0, 0); } while (0)
; #define PG8_LDA(dst, b, h) do { _Pragma("unroll") for (int m = 0; m < 4; ++m) _Pragma("unroll") for (int k = 0; k < 2; ++k) dst[m][k] = *(const PG8_LAS bf16x8*)(lds + PG8_SA(b, h) + aoff + m * 2048 + k * 1024); } while (0)
; #define PG8_LDB(dst, b, h) do { _Pragma("unroll") for (int n = 0; n < 2; ++n) _Pragma("unroll") for (int k = 0; k < 2; ++k) dst[n][k] = *(const PG8_LAS bf16x8*)(lds + PG8_SB(b, h) + boff + n * 2048 + k * 1024); } while (0)
; #define PG8_BAR __builtin_amdgcn_s_barrier()
; #define PG8_SCHED __builtin_amdgcn_sched_barrier(0)
; template <class Epi, class Sched, bool ALIGN_EPI = false, bool SP2 = false, bool ABLK = false, bool BBLK = false>
; __device__ __forceinline__ void gemm_phase(PG8_LAS unsigned char* lds, const Gemm g, const Sched& S, const Epi& E) {
;     ...
;         const bool has_next = S.next(ui + 1, nxt);
;         const char* nA = has_next ? (const char*)g.A + (size_t)nxt.pm * tstepA : cA; const char* nB = has_next ? (const char*)g.Bt + (size_t)nxt.pn * tstepB : cB;
;         for (int t = 0; t < nt; t += 2) {
;             const bool last = (t == nt - 2);
;             const char* a1 = cA + (size_t)(t + 1) * kstepA;
;             const char* a2 = last ? nA : cA + (size_t)(t + 2) * kstepA; const char* b2 = last ? nB : cB + (size_t)(t + 2) * kstepB;
;             const char* a3 = a2 + kstepA; const char* b3 = b2 + kstepB;
;             if (last && has_next) S.a_ready(nxt);
;             if constexpr (SP2) {
;             PG8_LDB(B0, 0, 0); PG8_LDB(B1, 0, 1); PG8_SCHED; PG8_LDA(At, 0, 0); PG8_STAGE(PG8_SA(1, 1), a1 + hstepA, voffA);
;     ...
; #pragma unroll
;         for (int a = 0; a < 2; ++a)
; #pragma unroll
;             for (int b = 0; b < 2; ++b)
; #pragma unroll
;                 for (int m = 0; m < 4; ++m)
; #pragma unroll
;                     for (int n = 0; n < 2; ++n) acc[a][b][m][n] = (f32x4){0.f, 0.f, 0.f, 0.f};
;         cur = nxt; cA = nA; cB = nB; ++ui;
;         if constexpr (ALIGN_EPI) { if (wr == 1) PG8_BAR; }
.LBB0_304:
	s_add_u32 s0, s0, 0xc000
	s_addc_u32 s1, s1, 0
	s_add_u32 s29, s34, 0x10000
	v_mov_b32_e32 v2, 0
	s_addc_u32 s31, s35, 0
	s_mov_b32 s33, -2
	s_and_b64 vcc, exec, s[18:19]
	s_cbranch_vccnz .Lrb_f1b0
	s_barrier
.Lrb_f1b0:
	s_add_u32 s8, s0, 0x4000
	s_addc_u32 s9, s1, 0
	s_cmpk_eq_i32 s33, 0x54
	s_cselect_b32 s36, s24, s8
	s_cselect_b32 s37, s25, s9
	s_cselect_b32 s34, s26, s29
	s_cselect_b32 s35, s27, s31
	s_add_u32 s8, s36, 0x8000
	s_addc_u32 s9, s37, 0
	s_add_i32 s40, 0, 0x10000
	s_add_i32 s44, 0, 0x14000
	v_add_u32_e32 v142, s40, v206
	v_add_u32_e32 v158, s44, v206
	ds_read_b128 v[130:133], v142
	v_pk_mov_b32 v[2:3], 0, 0
	v_pk_mov_b32 v[4:5], 0, 0
	v_pk_mov_b32 v[6:7], 0, 0
	v_pk_mov_b32 v[8:9], 0, 0
	ds_read_b128 v[134:137], v142 offset:1024
	v_pk_mov_b32 v[10:11], 0, 0
	v_pk_mov_b32 v[12:13], 0, 0
	v_pk_mov_b32 v[14:15], 0, 0
	v_pk_mov_b32 v[16:17], 0, 0
	ds_read_b128 v[138:141], v142 offset:2048
	v_pk_mov_b32 v[18:19], 0, 0
	v_pk_mov_b32 v[20:21], 0, 0
	v_pk_mov_b32 v[22:23], 0, 0
	v_pk_mov_b32 v[24:25], 0, 0
	ds_read_b128 v[142:145], v142 offset:3072
	v_pk_mov_b32 v[26:27], 0, 0
	v_pk_mov_b32 v[28:29], 0, 0
	v_pk_mov_b32 v[30:31], 0, 0
	v_pk_mov_b32 v[32:33], 0, 0
	ds_read_b128 v[146:149], v158
	v_pk_mov_b32 v[34:35], 0, 0
	v_pk_mov_b32 v[36:37], 0, 0
	v_pk_mov_b32 v[38:39], 0, 0
	v_pk_mov_b32 v[40:41], 0, 0
	ds_read_b128 v[150:153], v158 offset:1024
	v_pk_mov_b32 v[42:43], 0, 0
	v_pk_mov_b32 v[44:45], 0, 0
	v_pk_mov_b32 v[46:47], 0, 0
	v_pk_mov_b32 v[48:49], 0, 0
	ds_read_b128 v[154:157], v158 offset:2048
	v_pk_mov_b32 v[50:51], 0, 0
	v_pk_mov_b32 v[52:53], 0, 0
	v_pk_mov_b32 v[54:55], 0, 0
	v_pk_mov_b32 v[56:57], 0, 0
	ds_read_b128 v[158:161], v158 offset:3072
	v_pk_mov_b32 v[58:59], 0, 0
	v_pk_mov_b32 v[60:61], 0, 0
	v_pk_mov_b32 v[62:63], 0, 0
	v_pk_mov_b32 v[64:65], 0, 0
	v_lshl_add_u64 v[202:203], s[0:1], 0, v[184:185]
	s_add_i32 m0, s3, 0xc000
	ds_read_b128 v[162:165], v207
	v_pk_mov_b32 v[66:67], 0, 0
	v_pk_mov_b32 v[68:69], 0, 0
	v_pk_mov_b32 v[70:71], 0, 0
	v_pk_mov_b32 v[72:73], 0, 0
	ds_read_b128 v[166:169], v207 offset:1024
	v_pk_mov_b32 v[74:75], 0, 0
	v_pk_mov_b32 v[76:77], 0, 0
	v_pk_mov_b32 v[78:79], 0, 0
	v_pk_mov_b32 v[80:81], 0, 0
	ds_read_b128 v[170:173], v207 offset:2048
	v_pk_mov_b32 v[82:83], 0, 0
	v_pk_mov_b32 v[84:85], 0, 0
	v_pk_mov_b32 v[86:87], 0, 0
	v_pk_mov_b32 v[88:89], 0, 0
	ds_read_b128 v[174:177], v207 offset:3072
	v_pk_mov_b32 v[90:91], 0, 0
	v_pk_mov_b32 v[92:93], 0, 0
	v_pk_mov_b32 v[94:95], 0, 0
	v_pk_mov_b32 v[96:97], 0, 0
	ds_read_b128 v[198:201], v207 offset:4096
	v_pk_mov_b32 v[98:99], 0, 0
	v_pk_mov_b32 v[100:101], 0, 0
	v_pk_mov_b32 v[102:103], 0, 0
	v_pk_mov_b32 v[104:105], 0, 0
	ds_read_b128 v[208:211], v207 offset:5120
	v_pk_mov_b32 v[106:107], 0, 0
	v_pk_mov_b32 v[108:109], 0, 0
	v_pk_mov_b32 v[110:111], 0, 0
	v_pk_mov_b32 v[112:113], 0, 0
	ds_read_b128 v[212:215], v207 offset:6144
	v_pk_mov_b32 v[114:115], 0, 0
	v_pk_mov_b32 v[116:117], 0, 0
	v_pk_mov_b32 v[118:119], 0, 0
	v_pk_mov_b32 v[120:121], 0, 0
	ds_read_b128 v[216:219], v207 offset:7168
	v_pk_mov_b32 v[122:123], 0, 0
	v_pk_mov_b32 v[124:125], 0, 0
	v_pk_mov_b32 v[126:127], 0, 0
	v_pk_mov_b32 v[128:129], 0, 0
	global_load_lds_dwordx4 v[202:203], off
	v_lshl_add_u64 v[202:203], s[0:1], 0, v[196:197]
	s_add_i32 m0, s3, 0xe000
	s_nop 0
	global_load_lds_dwordx4 v[202:203], off
	s_waitcnt vmcnt(8)
	s_waitcnt lgkmcnt(0)
	s_barrier
	s_branch .Lpeel_305

; #define PG8_STAGE(bufoff, gbase, voff) do { _Pragma("unroll") for (int _i = 0; _i < 2; ++_i) \
;         __builtin_amdgcn_global_load_lds((const unsigned*)((const char*)(gbase) + (voff)[_i]), (PG8_LAS unsigned*)(lds + (bufoff) + ldsw + _i * 8192), 16, 0, 0); } while (0)
; #define PG8_LDA(dst, b, h) do { _Pragma("unroll") for (int m = 0; m < 4; ++m) _Pragma("unroll") for (int k = 0; k < 2; ++k) dst[m][k] = *(const PG8_LAS bf16x8*)(lds + PG8_SA(b, h) + aoff + m * 2048 + k * 1024); } while (0)
; #define PG8_LDB(dst, b, h) do { _Pragma("unroll") for (int n = 0; n < 2; ++n) _Pragma("unroll") for (int k = 0; k < 2; ++k) dst[n][k] = *(const PG8_LAS bf16x8*)(lds + PG8_SB(b, h) + boff + n * 2048 + k * 1024); } while (0)
; #define PG8_BAR __builtin_amdgcn_s_barrier()
; #define PG8_SCHED __builtin_amdgcn_sched_barrier(0)
; template <class Epi, class Sched, bool ALIGN_EPI = false, bool SP2 = false, bool ABLK = false, bool BBLK = false>
; __device__ __forceinline__ void gemm_phase(PG8_LAS unsigned char* lds, const Gemm g, const Sched& S, const Epi& E) {
;     ...
;         const bool has_next = S.next(ui + 1, nxt);
;         const char* nA = has_next ? (const char*)g.A + (size_t)nxt.pm * tstepA : cA; const char* nB = has_next ? (const char*)g.Bt + (size_t)nxt.pn * tstepB : cB;
;         for (int t = 0; t < nt; t += 2) {
;             const bool last = (t == nt - 2);
;             const char* a1 = cA + (size_t)(t + 1) * kstepA;
;             const char* a2 = last ? nA : cA + (size_t)(t + 2) * kstepA; const char* b2 = last ? nB : cB + (size_t)(t + 2) * kstepB;
;             const char* a3 = a2 + kstepA; const char* b3 = b2 + kstepB;
;             if (last && has_next) S.a_ready(nxt);
;             if constexpr (SP2) {
;             PG8_LDB(B0, 0, 0); PG8_LDB(B1, 0, 1); PG8_SCHED; PG8_LDA(At, 0, 0); PG8_STAGE(PG8_SA(1, 1), a1 + hstepA, voffA);
;     ...
; #pragma unroll
;         for (int a = 0; a < 2; ++a)
; #pragma unroll
;             for (int b = 0; b < 2; ++b)
; #pragma unroll
;                 for (int m = 0; m < 4; ++m)
; #pragma unroll
;                     for (int n = 0; n < 2; ++n) acc[a][b][m][n] = (f32x4){0.f, 0.f, 0.f, 0.f};
;         cur = nxt; cA = nA; cB = nB; ++ui;
;         if constexpr (ALIGN_EPI) { if (wr == 1) PG8_BAR; }
.LBB0_366:
	s_add_u32 s0, s0, 0xc000
	s_addc_u32 s1, s1, 0
	s_add_u32 s29, s34, 0x10000
	v_mov_b32_e32 v66, 0
	s_addc_u32 s31, s35, 0
	s_mov_b32 s33, -2
	s_and_b64 vcc, exec, s[18:19]
	s_cbranch_vccnz .Lrb_f1b1
	s_barrier
.Lrb_f1b1:
	s_add_u32 s8, s0, 0x4000
	s_addc_u32 s9, s1, 0
	s_cmpk_eq_i32 s33, 0x54
	s_cselect_b32 s36, s24, s8
	s_cselect_b32 s37, s25, s9
	s_cselect_b32 s34, s26, s29
	s_cselect_b32 s35, s27, s31
	s_add_u32 s8, s36, 0x8000
	s_addc_u32 s9, s37, 0
	s_add_i32 s40, 0, 0x10000
	s_add_i32 s44, 0, 0x14000
	v_add_u32_e32 v142, s40, v206
	v_add_u32_e32 v158, s44, v206
	ds_read_b128 v[26:29], v142
	v_pk_mov_b32 v[2:3], 0, 0
	v_pk_mov_b32 v[4:5], 0, 0
	v_pk_mov_b32 v[6:7], 0, 0
	v_pk_mov_b32 v[8:9], 0, 0
	ds_read_b128 v[30:33], v142 offset:1024
	v_pk_mov_b32 v[10:11], 0, 0
	v_pk_mov_b32 v[12:13], 0, 0
	v_pk_mov_b32 v[14:15], 0, 0
	v_pk_mov_b32 v[16:17], 0, 0
	ds_read_b128 v[138:141], v142 offset:2048
	v_pk_mov_b32 v[18:19], 0, 0
	v_pk_mov_b32 v[20:21], 0, 0
	v_pk_mov_b32 v[22:23], 0, 0
	v_pk_mov_b32 v[24:25], 0, 0
	ds_read_b128 v[142:145], v142 offset:3072
	v_pk_mov_b32 v[34:35], 0, 0
	v_pk_mov_b32 v[36:37], 0, 0
	v_pk_mov_b32 v[38:39], 0, 0
	v_pk_mov_b32 v[40:41], 0, 0
	ds_read_b128 v[146:149], v158
	v_pk_mov_b32 v[42:43], 0, 0
	v_pk_mov_b32 v[44:45], 0, 0
	v_pk_mov_b32 v[46:47], 0, 0
	v_pk_mov_b32 v[48:49], 0, 0
	ds_read_b128 v[150:153], v158 offset:1024
	v_pk_mov_b32 v[50:51], 0, 0
	v_pk_mov_b32 v[52:53], 0, 0
	v_pk_mov_b32 v[54:55], 0, 0
	v_pk_mov_b32 v[56:57], 0, 0
	ds_read_b128 v[154:157], v158 offset:2048
	v_pk_mov_b32 v[58:59], 0, 0
	v_pk_mov_b32 v[60:61], 0, 0
	v_pk_mov_b32 v[62:63], 0, 0
	v_pk_mov_b32 v[64:65], 0, 0
	ds_read_b128 v[158:161], v158 offset:3072
	v_pk_mov_b32 v[66:67], 0, 0
	v_pk_mov_b32 v[68:69], 0, 0
	v_pk_mov_b32 v[70:71], 0, 0
	v_pk_mov_b32 v[72:73], 0, 0
	v_lshl_add_u64 v[202:203], s[0:1], 0, v[184:185]
	s_add_i32 m0, s83, 0xc000
	ds_read_b128 v[162:165], v207
	v_pk_mov_b32 v[74:75], 0, 0
	v_pk_mov_b32 v[76:77], 0, 0
	v_pk_mov_b32 v[78:79], 0, 0
	v_pk_mov_b32 v[80:81], 0, 0
	ds_read_b128 v[166:169], v207 offset:1024
	v_pk_mov_b32 v[82:83], 0, 0
	v_pk_mov_b32 v[84:85], 0, 0
	v_pk_mov_b32 v[86:87], 0, 0
	v_pk_mov_b32 v[88:89], 0, 0
	ds_read_b128 v[170:173], v207 offset:2048
	v_pk_mov_b32 v[90:91], 0, 0
	v_pk_mov_b32 v[92:93], 0, 0
	v_pk_mov_b32 v[94:95], 0, 0
	v_pk_mov_b32 v[96:97], 0, 0
	ds_read_b128 v[174:177], v207 offset:3072
	v_pk_mov_b32 v[98:99], 0, 0
	v_pk_mov_b32 v[100:101], 0, 0
	v_pk_mov_b32 v[102:103], 0, 0
	v_pk_mov_b32 v[104:105], 0, 0
	ds_read_b128 v[198:201], v207 offset:4096
	v_pk_mov_b32 v[106:107], 0, 0
	v_pk_mov_b32 v[108:109], 0, 0
	v_pk_mov_b32 v[110:111], 0, 0
	v_pk_mov_b32 v[112:113], 0, 0
	ds_read_b128 v[208:211], v207 offset:5120
	v_pk_mov_b32 v[114:115], 0, 0
	v_pk_mov_b32 v[116:117], 0, 0
	v_pk_mov_b32 v[118:119], 0, 0
	v_pk_mov_b32 v[120:121], 0, 0
	ds_read_b128 v[212:215], v207 offset:6144
	v_pk_mov_b32 v[122:123], 0, 0
	v_pk_mov_b32 v[124:125], 0, 0
	v_pk_mov_b32 v[126:127], 0, 0
	v_pk_mov_b32 v[128:129], 0, 0
	ds_read_b128 v[216:219], v207 offset:7168
	v_pk_mov_b32 v[130:131], 0, 0
	v_pk_mov_b32 v[132:133], 0, 0
	v_pk_mov_b32 v[134:135], 0, 0
	v_pk_mov_b32 v[136:137], 0, 0
	global_load_lds_dwordx4 v[202:203], off
	v_lshl_add_u64 v[202:203], s[0:1], 0, v[196:197]
	s_add_i32 m0, s83, 0xe000
	s_nop 0
	global_load_lds_dwordx4 v[202:203], off
	s_waitcnt vmcnt(8)
	s_waitcnt lgkmcnt(0)
	s_barrier
	s_branch .Lpeel_367

; #define PG8_STAGE(bufoff, gbase, voff) do { _Pragma("unroll") for (int _i = 0; _i < 2; ++_i) \
;         __builtin_amdgcn_global_load_lds((const unsigned*)((const char*)(gbase) + (voff)[_i]), (PG8_LAS unsigned*)(lds + (bufoff) + ldsw + _i * 8192), 16, 0, 0); } while (0)
; #define PG8_LDA(dst, b, h) do { _Pragma("unroll") for (int m = 0; m < 4; ++m) _Pragma("unroll") for (int k = 0; k < 2; ++k) dst[m][k] = *(const PG8_LAS bf16x8*)(lds + PG8_SA(b, h) + aoff + m * 2048 + k * 1024); } while (0)
; #define PG8_LDB(dst, b, h) do { _Pragma("unroll") for (int n = 0; n < 2; ++n) _Pragma("unroll") for (int k = 0; k < 2; ++k) dst[n][k] = *(const PG8_LAS bf16x8*)(lds + PG8_SB(b, h) + boff + n * 2048 + k * 1024); } while (0)
; #define PG8_BAR __builtin_amdgcn_s_barrier()
; #define PG8_SCHED __builtin_amdgcn_sched_barrier(0)
; template <class Epi, class Sched, bool ALIGN_EPI = false, bool SP2 = false, bool ABLK = false, bool BBLK = false>
; __device__ __forceinline__ void gemm_phase(PG8_LAS unsigned char* lds, const Gemm g, const Sched& S, const Epi& E) {
;     ...
;         const bool has_next = S.next(ui + 1, nxt);
;         const char* nA = has_next ? (const char*)g.A + (size_t)nxt.pm * tstepA : cA; const char* nB = has_next ? (const char*)g.Bt + (size_t)nxt.pn * tstepB : cB;
;         for (int t = 0; t < nt; t += 2) {
;             const bool last = (t == nt - 2);
;             const char* a1 = cA + (size_t)(t + 1) * kstepA;
;             const char* a2 = last ? nA : cA + (size_t)(t + 2) * kstepA; const char* b2 = last ? nB : cB + (size_t)(t + 2) * kstepB;
;             const char* a3 = a2 + kstepA; const char* b3 = b2 + kstepB;
;             if (last && has_next) S.a_ready(nxt);
;             if constexpr (SP2) {
;             PG8_LDB(B0, 0, 0); PG8_LDB(B1, 0, 1); PG8_SCHED; PG8_LDA(At, 0, 0); PG8_STAGE(PG8_SA(1, 1), a1 + hstepA, voffA);
;     ...
; #pragma unroll
;         for (int a = 0; a < 2; ++a)
; #pragma unroll
;             for (int b = 0; b < 2; ++b)
; #pragma unroll
;                 for (int m = 0; m < 4; ++m)
; #pragma unroll
;                     for (int n = 0; n < 2; ++n) acc[a][b][m][n] = (f32x4){0.f, 0.f, 0.f, 0.f};
;         cur = nxt; cA = nA; cB = nB; ++ui;
;         if constexpr (ALIGN_EPI) { if (wr == 1) PG8_BAR; }
.LBB0_593:
	s_ashr_i32 s21, s20, 31
	s_lshl_b64 s[24:25], s[20:21], 20
	s_add_u32 s24, s51, s24
	s_addc_u32 s25, s53, s25
	s_and_b64 s[26:27], s[6:7], exec
	s_cselect_b32 s9, s25, s1
	s_cselect_b32 s16, s24, s0
	s_ashr_i32 s23, s22, 31
	s_lshl_b64 s[26:27], s[22:23], 20
	s_add_u32 s26, s44, s26
	s_addc_u32 s27, s45, s27
	s_and_b64 s[34:35], s[6:7], exec
	s_cselect_b32 s21, s27, s31
	s_cselect_b32 s23, s26, s30
	s_add_u32 s0, s0, 0xc000
	s_addc_u32 s1, s1, 0
	s_add_u32 s29, s30, 0x10000
	v_mov_b32_e32 v2, 0
	s_addc_u32 s40, s31, 0
	s_mov_b32 s41, -2
	v_mov_b32_e32 v3, v2
	v_mov_b32_e32 v4, v2
	v_mov_b32_e32 v5, v2
	v_mov_b32_e32 v6, v2
	v_mov_b32_e32 v7, v2
	v_mov_b32_e32 v8, v2
	v_mov_b32_e32 v9, v2
	s_waitcnt vmcnt(0)
	s_and_b64 vcc, exec, s[18:19]
	s_cbranch_vccnz .Lrb_ma
	s_barrier
.Lrb_ma:
	s_add_u32 s30, s0, 0x4000
	s_addc_u32 s31, s1, 0
	s_cmp_eq_u32 s41, 28
	s_cselect_b32 s36, s16, s30
	s_cselect_b32 s37, s9, s31
	s_cselect_b32 s34, s23, s29
	s_cselect_b32 s35, s21, s40
	s_add_u32 s30, s36, 0x8000
	s_addc_u32 s31, s37, 0
	s_add_i32 s60, 0, 0x10000
	s_add_i32 s75, 0, 0x14000
	v_add_u32_e32 v142, s60, v169
	v_add_u32_e32 v171, s75, v169
	ds_read_b128 v[130:133], v142
	v_pk_mov_b32 v[10:11], 0, 0
	v_pk_mov_b32 v[12:13], 0, 0
	v_pk_mov_b32 v[14:15], 0, 0
	v_pk_mov_b32 v[16:17], 0, 0
	ds_read_b128 v[134:137], v142 offset:1024
	v_pk_mov_b32 v[18:19], 0, 0
	v_pk_mov_b32 v[20:21], 0, 0
	v_pk_mov_b32 v[22:23], 0, 0
	v_pk_mov_b32 v[24:25], 0, 0
	ds_read_b128 v[138:141], v142 offset:2048
	v_pk_mov_b32 v[26:27], 0, 0
	v_pk_mov_b32 v[28:29], 0, 0
	v_pk_mov_b32 v[30:31], 0, 0
	v_pk_mov_b32 v[32:33], 0, 0
	ds_read_b128 v[142:145], v142 offset:3072
	v_pk_mov_b32 v[34:35], 0, 0
	v_pk_mov_b32 v[36:37], 0, 0
	v_pk_mov_b32 v[38:39], 0, 0
	v_pk_mov_b32 v[40:41], 0, 0
	ds_read_b128 v[160:163], v171
	v_pk_mov_b32 v[42:43], 0, 0
	v_pk_mov_b32 v[44:45], 0, 0
	v_pk_mov_b32 v[46:47], 0, 0
	v_pk_mov_b32 v[48:49], 0, 0
	ds_read_b128 v[164:167], v171 offset:1024
	v_pk_mov_b32 v[50:51], 0, 0
	v_pk_mov_b32 v[52:53], 0, 0
	v_pk_mov_b32 v[54:55], 0, 0
	v_pk_mov_b32 v[56:57], 0, 0
	ds_read_b128 v[172:175], v171 offset:2048
	v_pk_mov_b32 v[58:59], 0, 0
	v_pk_mov_b32 v[60:61], 0, 0
	v_pk_mov_b32 v[62:63], 0, 0
	v_pk_mov_b32 v[64:65], 0, 0
	ds_read_b128 v[176:179], v171 offset:3072
	v_pk_mov_b32 v[66:67], 0, 0
	v_pk_mov_b32 v[68:69], 0, 0
	v_pk_mov_b32 v[70:71], 0, 0
	v_pk_mov_b32 v[72:73], 0, 0
	v_lshl_add_u64 v[184:185], s[0:1], 0, v[156:157]
	s_add_i32 m0, s83, 0xc000
	ds_read_b128 v[180:183], v170
	v_pk_mov_b32 v[74:75], 0, 0
	v_pk_mov_b32 v[76:77], 0, 0
	v_pk_mov_b32 v[78:79], 0, 0
	v_pk_mov_b32 v[80:81], 0, 0
	ds_read_b128 v[196:199], v170 offset:1024
	v_pk_mov_b32 v[82:83], 0, 0
	v_pk_mov_b32 v[84:85], 0, 0
	v_pk_mov_b32 v[86:87], 0, 0
	v_pk_mov_b32 v[88:89], 0, 0
	ds_read_b128 v[200:203], v170 offset:2048
	v_pk_mov_b32 v[90:91], 0, 0
	v_pk_mov_b32 v[92:93], 0, 0
	v_pk_mov_b32 v[94:95], 0, 0
	v_pk_mov_b32 v[96:97], 0, 0
	ds_read_b128 v[204:207], v170 offset:3072
	v_pk_mov_b32 v[98:99], 0, 0
	v_pk_mov_b32 v[100:101], 0, 0
	v_pk_mov_b32 v[102:103], 0, 0
	v_pk_mov_b32 v[104:105], 0, 0
	ds_read_b128 v[208:211], v170 offset:4096
	v_pk_mov_b32 v[106:107], 0, 0
	v_pk_mov_b32 v[108:109], 0, 0
	v_pk_mov_b32 v[110:111], 0, 0
	v_pk_mov_b32 v[112:113], 0, 0
	ds_read_b128 v[212:215], v170 offset:5120
	v_pk_mov_b32 v[114:115], 0, 0
	v_pk_mov_b32 v[116:117], 0, 0
	v_pk_mov_b32 v[118:119], 0, 0
	v_pk_mov_b32 v[120:121], 0, 0
	ds_read_b128 v[216:219], v170 offset:6144
	v_pk_mov_b32 v[122:123], 0, 0
	v_pk_mov_b32 v[124:125], 0, 0
	v_pk_mov_b32 v[126:127], 0, 0
	v_pk_mov_b32 v[128:129], 0, 0
	ds_read_b128 v[220:223], v170 offset:7168
	global_load_lds_dwordx4 v[184:185], off
	v_lshl_add_u64 v[184:185], s[0:1], 0, v[158:159]
	s_add_i32 m0, s83, 0xe000
	s_nop 0
	global_load_lds_dwordx4 v[184:185], off
	s_waitcnt vmcnt(8)
	s_waitcnt lgkmcnt(0)
	s_barrier
	s_branch .Lpeel_594

; #define PG8_STAGE(bufoff, gbase, voff) do { _Pragma("unroll") for (int _i = 0; _i < 2; ++_i) \
;         __builtin_amdgcn_global_load_lds((const unsigned*)((const char*)(gbase) + (voff)[_i]), (PG8_LAS unsigned*)(lds + (bufoff) + ldsw + _i * 8192), 16, 0, 0); } while (0)
; #define PG8_LDA(dst, b, h) do { _Pragma("unroll") for (int m = 0; m < 4; ++m) _Pragma("unroll") for (int k = 0; k < 2; ++k) dst[m][k] = *(const PG8_LAS bf16x8*)(lds + PG8_SA(b, h) + aoff + m * 2048 + k * 1024); } while (0)
; #define PG8_LDB(dst, b, h) do { _Pragma("unroll") for (int n = 0; n < 2; ++n) _Pragma("unroll") for (int k = 0; k < 2; ++k) dst[n][k] = *(const PG8_LAS bf16x8*)(lds + PG8_SB(b, h) + boff + n * 2048 + k * 1024); } while (0)
; #define PG8_WAIT_V(n) asm volatile("s_waitcnt vmcnt(" #n ")" ::: "memory")
; #define PG8_WAIT_L(n) asm volatile("s_waitcnt lgkmcnt(" #n ")" ::: "memory")
; template <class Epi, class Sched, bool ALIGN_EPI = false, bool SP2 = false, bool ABLK = false, bool BBLK = false>
; __device__ __forceinline__ void gemm_phase(PG8_LAS unsigned char* lds, const Gemm g, const Sched& S, const Epi& E) {
;     ...
;         const char* nA = has_next ? (const char*)g.A + (size_t)nxt.pm * tstepA : cA; const char* nB = has_next ? (const char*)g.Bt + (size_t)nxt.pn * tstepB : cB;
;         for (int t = 0; t < nt; t += 2) {
;             const bool last = (t == nt - 2);
;             const char* a1 = cA + (size_t)(t + 1) * kstepA;
;             const char* a2 = last ? nA : cA + (size_t)(t + 2) * kstepA; const char* b2 = last ? nB : cB + (size_t)(t + 2) * kstepB;
;             const char* a3 = a2 + kstepA; const char* b3 = b2 + kstepB;
;             if (last && has_next) S.a_ready(nxt);
;             if constexpr (SP2) {
;             PG8_LDB(B0, 0, 0); PG8_LDB(B1, 0, 1); PG8_SCHED; PG8_LDA(At, 0, 0); PG8_STAGE(PG8_SA(1, 1), a1 + hstepA, voffA);
;             PG8_WAIT_V(8); PG8_WAIT_L(0); PG8_BAR; PG8_MMA(0, 0, At, B0); PG8_MMA(0, 1, At, B1); PG8_BAR; PG8_SCHED;
;     ...
; #pragma unroll
;         for (int a = 0; a < 2; ++a)
; #pragma unroll
;             for (int b = 0; b < 2; ++b)
; #pragma unroll
;                 for (int m = 0; m < 4; ++m)
; #pragma unroll
;                     for (int n = 0; n < 2; ++n) acc[a][b][m][n] = (f32x4){0.f, 0.f, 0.f, 0.f};
;         cur = nxt; cA = nA; cB = nB; ++ui;
;         if constexpr (ALIGN_EPI) { if (wr == 1) PG8_BAR; }
.LBB0_657:
	s_ashr_i32 s13, s12, 31
	s_lshl_b64 s[14:15], s[12:13], 20
	s_add_u32 s14, s31, s14
	s_addc_u32 s15, s33, s15
	s_and_b64 s[18:19], s[6:7], exec
	s_cselect_b32 s13, s15, s23
	s_cselect_b32 s61, s14, s22
	s_ashr_i32 s1, s0, 31
	s_lshl_b64 s[18:19], s[0:1], 20
	s_add_u32 s18, s51, s18
	s_addc_u32 s19, s53, s19
	s_and_b64 s[26:27], s[6:7], exec
	s_cselect_b32 s1, s19, s25
	s_cselect_b32 s65, s18, s24
	s_add_u32 s22, s22, 0xc000
	s_addc_u32 s23, s23, 0
	s_add_u32 s68, s24, 0x10000
	v_mov_b32_e32 v2, 0
	s_addc_u32 s72, s25, 0
	s_mov_b32 s73, -2
	s_and_b64 vcc, exec, s[8:9]
	s_cbranch_vccnz .Lrb_fold
	s_barrier
.Lrb_fold:
	s_add_u32 s24, s22, 0x4000
	s_addc_u32 s25, s23, 0
	s_cmp_eq_u32 s73, 28
	s_cselect_b32 s28, s61, s24
	s_cselect_b32 s29, s13, s25
	s_cselect_b32 s26, s65, s68
	s_cselect_b32 s27, s1, s72
	s_add_u32 s24, s28, 0x8000
	s_addc_u32 s25, s29, 0
	s_add_i32 s75, 0, 0x10000
	s_add_i32 s82, 0, 0x14000
	v_add_u32_e32 v158, s75, v147
	v_add_u32_e32 v174, s82, v147
	ds_read_b128 v[142:145], v158
	v_pk_mov_b32 v[2:3], 0, 0
	v_pk_mov_b32 v[4:5], 0, 0
	v_pk_mov_b32 v[6:7], 0, 0
	v_pk_mov_b32 v[8:9], 0, 0
	ds_read_b128 v[150:153], v158 offset:1024
	v_pk_mov_b32 v[10:11], 0, 0
	v_pk_mov_b32 v[12:13], 0, 0
	v_pk_mov_b32 v[14:15], 0, 0
	v_pk_mov_b32 v[16:17], 0, 0
	ds_read_b128 v[154:157], v158 offset:2048
	v_pk_mov_b32 v[18:19], 0, 0
	v_pk_mov_b32 v[20:21], 0, 0
	v_pk_mov_b32 v[22:23], 0, 0
	v_pk_mov_b32 v[24:25], 0, 0
	ds_read_b128 v[158:161], v158 offset:3072
	v_pk_mov_b32 v[26:27], 0, 0
	v_pk_mov_b32 v[28:29], 0, 0
	v_pk_mov_b32 v[30:31], 0, 0
	v_pk_mov_b32 v[32:33], 0, 0
	ds_read_b128 v[162:165], v174
	v_pk_mov_b32 v[34:35], 0, 0
	v_pk_mov_b32 v[36:37], 0, 0
	v_pk_mov_b32 v[38:39], 0, 0
	v_pk_mov_b32 v[40:41], 0, 0
	ds_read_b128 v[166:169], v174 offset:1024
	v_pk_mov_b32 v[42:43], 0, 0
	v_pk_mov_b32 v[44:45], 0, 0
	v_pk_mov_b32 v[46:47], 0, 0
	v_pk_mov_b32 v[48:49], 0, 0
	ds_read_b128 v[170:173], v174 offset:2048
	v_pk_mov_b32 v[50:51], 0, 0
	v_pk_mov_b32 v[52:53], 0, 0
	v_pk_mov_b32 v[54:55], 0, 0
	v_pk_mov_b32 v[56:57], 0, 0
	ds_read_b128 v[174:177], v174 offset:3072
	v_pk_mov_b32 v[58:59], 0, 0
	v_pk_mov_b32 v[60:61], 0, 0
	v_pk_mov_b32 v[62:63], 0, 0
	v_pk_mov_b32 v[64:65], 0, 0
	v_lshl_add_u64 v[220:221], s[22:23], 0, v[138:139]
	s_add_i32 m0, s40, 0xc000
	ds_read_b128 v[178:181], v149
	v_pk_mov_b32 v[66:67], 0, 0
	v_pk_mov_b32 v[68:69], 0, 0
	v_pk_mov_b32 v[70:71], 0, 0
	v_pk_mov_b32 v[72:73], 0, 0
	ds_read_b128 v[182:185], v149 offset:1024
	v_pk_mov_b32 v[74:75], 0, 0
	v_pk_mov_b32 v[76:77], 0, 0
	v_pk_mov_b32 v[78:79], 0, 0
	v_pk_mov_b32 v[80:81], 0, 0
	ds_read_b128 v[196:199], v149 offset:2048
	v_pk_mov_b32 v[82:83], 0, 0
	v_pk_mov_b32 v[84:85], 0, 0
	v_pk_mov_b32 v[86:87], 0, 0
	v_pk_mov_b32 v[88:89], 0, 0
	ds_read_b128 v[200:203], v149 offset:3072
	v_pk_mov_b32 v[90:91], 0, 0
	v_pk_mov_b32 v[92:93], 0, 0
	v_pk_mov_b32 v[94:95], 0, 0
	v_pk_mov_b32 v[96:97], 0, 0
	ds_read_b128 v[204:207], v149 offset:4096
	v_pk_mov_b32 v[98:99], 0, 0
	v_pk_mov_b32 v[100:101], 0, 0
	v_pk_mov_b32 v[102:103], 0, 0
	v_pk_mov_b32 v[104:105], 0, 0
	ds_read_b128 v[208:211], v149 offset:5120
	v_pk_mov_b32 v[106:107], 0, 0
	v_pk_mov_b32 v[108:109], 0, 0
	v_pk_mov_b32 v[110:111], 0, 0
	v_pk_mov_b32 v[112:113], 0, 0
	ds_read_b128 v[212:215], v149 offset:6144
	v_pk_mov_b32 v[114:115], 0, 0
	v_pk_mov_b32 v[116:117], 0, 0
	v_pk_mov_b32 v[118:119], 0, 0
	v_pk_mov_b32 v[120:121], 0, 0
	ds_read_b128 v[216:219], v149 offset:7168
	v_pk_mov_b32 v[122:123], 0, 0
	v_pk_mov_b32 v[124:125], 0, 0
	v_pk_mov_b32 v[126:127], 0, 0
	v_pk_mov_b32 v[128:129], 0, 0
	global_load_lds_dwordx4 v[220:221], off
	v_lshl_add_u64 v[220:221], s[22:23], 0, v[140:141]
	s_add_i32 m0, s40, 0xe000
	s_nop 0
	global_load_lds_dwordx4 v[220:221], off
	s_waitcnt vmcnt(8)
	s_waitcnt lgkmcnt(0)
	s_barrier
	s_branch .Lpeel_658

; #define PG8_STAGE(bufoff, gbase, voff) do { _Pragma("unroll") for (int _i = 0; _i < 2; ++_i) \
;         __builtin_amdgcn_global_load_lds((const unsigned*)((const char*)(gbase) + (voff)[_i]), (PG8_LAS unsigned*)(lds + (bufoff) + ldsw + _i * 8192), 16, 0, 0); } while (0)
; #define PG8_LDA(dst, b, h) do { _Pragma("unroll") for (int m = 0; m < 4; ++m) _Pragma("unroll") for (int k = 0; k < 2; ++k) dst[m][k] = *(const PG8_LAS bf16x8*)(lds + PG8_SA(b, h) + aoff + m * 2048 + k * 1024); } while (0)
; #define PG8_LDB(dst, b, h) do { _Pragma("unroll") for (int n = 0; n < 2; ++n) _Pragma("unroll") for (int k = 0; k < 2; ++k) dst[n][k] = *(const PG8_LAS bf16x8*)(lds + PG8_SB(b, h) + boff + n * 2048 + k * 1024); } while (0)
; #define PG8_WAIT_V(n) asm volatile("s_waitcnt vmcnt(" #n ")" ::: "memory")
; #define PG8_WAIT_L(n) asm volatile("s_waitcnt lgkmcnt(" #n ")" ::: "memory")
; template <class Epi, class Sched, bool ALIGN_EPI = false, bool SP2 = false, bool ABLK = false, bool BBLK = false>
; __device__ __forceinline__ void gemm_phase(PG8_LAS unsigned char* lds, const Gemm g, const Sched& S, const Epi& E) {
;     ...
;         const char* nA = has_next ? (const char*)g.A + (size_t)nxt.pm * tstepA : cA; const char* nB = has_next ? (const char*)g.Bt + (size_t)nxt.pn * tstepB : cB;
;         for (int t = 0; t < nt; t += 2) {
;             const bool last = (t == nt - 2);
;             const char* a1 = cA + (size_t)(t + 1) * kstepA;
;             const char* a2 = last ? nA : cA + (size_t)(t + 2) * kstepA; const char* b2 = last ? nB : cB + (size_t)(t + 2) * kstepB;
;             const char* a3 = a2 + kstepA; const char* b3 = b2 + kstepB;
;             if (last && has_next) S.a_ready(nxt);
;             if constexpr (SP2) {
;             PG8_LDB(B0, 0, 0); PG8_LDB(B1, 0, 1); PG8_SCHED; PG8_LDA(At, 0, 0); PG8_STAGE(PG8_SA(1, 1), a1 + hstepA, voffA);
;             PG8_WAIT_V(8); PG8_WAIT_L(0); PG8_BAR; PG8_MMA(0, 0, At, B0); PG8_MMA(0, 1, At, B1); PG8_BAR; PG8_SCHED;
;     ...
; #pragma unroll
;         for (int a = 0; a < 2; ++a)
; #pragma unroll
;             for (int b = 0; b < 2; ++b)
; #pragma unroll
;                 for (int m = 0; m < 4; ++m)
; #pragma unroll
;                     for (int n = 0; n < 2; ++n) acc[a][b][m][n] = (f32x4){0.f, 0.f, 0.f, 0.f};
;         cur = nxt; cA = nA; cB = nB; ++ui;
;         if constexpr (ALIGN_EPI) { if (wr == 1) PG8_BAR; }
.LBB0_765:
	s_ashr_i32 s15, s14, 31
	s_lshl_b64 s[18:19], s[14:15], 20
	s_add_u32 s18, s33, s18
	s_addc_u32 s19, s34, s19
	s_and_b64 s[20:21], s[6:7], exec
	s_cselect_b32 s1, s19, s25
	s_cselect_b32 s11, s18, s24
	s_ashr_i32 s13, s12, 31
	s_lshl_b64 s[20:21], s[12:13], 20
	s_add_u32 s20, s35, s20
	s_addc_u32 s21, s36, s21
	s_and_b64 s[28:29], s[6:7], exec
	s_cselect_b32 s13, s21, s27
	s_cselect_b32 s15, s20, s26
	s_add_u32 s24, s24, 0x80080
	s_addc_u32 s25, s25, 0
	s_add_u32 s23, s26, 0x100
	v_mov_b32_e32 v2, 0
	s_addc_u32 s65, s27, 0
	s_mov_b32 s68, -2
	s_and_b64 vcc, exec, s[8:9]
	s_cbranch_vccnz .Lrb_dft0
	s_barrier
.Lrb_dft0:
	s_add_u32 s26, s24, 0xfff80080
	s_addc_u32 s27, s25, -1
	s_add_i32 s72, 0, 0x10000
	s_cmp_eq_u32 s68, 28
	s_cselect_b32 s29, s1, s27
	s_cselect_b32 s28, s11, s26
	v_add_u32_e32 v142, s72, v145
	s_cselect_b32 s27, s13, s65
	s_cselect_b32 s26, s15, s23
	s_add_i32 s75, 0, 0x14000
	ds_read_b128 v[148:151], v142
	v_pk_mov_b32 v[2:3], 0, 0
	v_pk_mov_b32 v[4:5], 0, 0
	v_pk_mov_b32 v[6:7], 0, 0
	v_pk_mov_b32 v[8:9], 0, 0
	ds_read_b128 v[152:155], v142 offset:1024
	v_pk_mov_b32 v[10:11], 0, 0
	v_pk_mov_b32 v[12:13], 0, 0
	v_pk_mov_b32 v[14:15], 0, 0
	v_pk_mov_b32 v[16:17], 0, 0
	ds_read_b128 v[156:159], v142 offset:2048
	v_pk_mov_b32 v[18:19], 0, 0
	v_pk_mov_b32 v[20:21], 0, 0
	v_pk_mov_b32 v[22:23], 0, 0
	v_pk_mov_b32 v[24:25], 0, 0
	ds_read_b128 v[160:163], v142 offset:3072
	v_pk_mov_b32 v[26:27], 0, 0
	v_pk_mov_b32 v[28:29], 0, 0
	v_pk_mov_b32 v[30:31], 0, 0
	v_pk_mov_b32 v[32:33], 0, 0
	v_add_u32_e32 v142, s75, v145
	ds_read_b128 v[164:167], v142
	v_pk_mov_b32 v[34:35], 0, 0
	v_pk_mov_b32 v[36:37], 0, 0
	v_pk_mov_b32 v[38:39], 0, 0
	v_pk_mov_b32 v[40:41], 0, 0
	ds_read_b128 v[168:171], v142 offset:1024
	v_pk_mov_b32 v[42:43], 0, 0
	v_pk_mov_b32 v[44:45], 0, 0
	v_pk_mov_b32 v[46:47], 0, 0
	v_pk_mov_b32 v[48:49], 0, 0
	ds_read_b128 v[172:175], v142 offset:2048
	v_pk_mov_b32 v[50:51], 0, 0
	v_pk_mov_b32 v[52:53], 0, 0
	v_pk_mov_b32 v[54:55], 0, 0
	v_pk_mov_b32 v[56:57], 0, 0
	ds_read_b128 v[176:179], v142 offset:3072
	v_pk_mov_b32 v[58:59], 0, 0
	v_pk_mov_b32 v[60:61], 0, 0
	v_pk_mov_b32 v[62:63], 0, 0
	v_pk_mov_b32 v[64:65], 0, 0
	v_lshl_add_u64 v[142:143], s[24:25], 0, v[138:139]
	s_add_i32 m0, s45, 0xc000
	ds_read_b128 v[180:183], v146
	v_pk_mov_b32 v[66:67], 0, 0
	v_pk_mov_b32 v[68:69], 0, 0
	v_pk_mov_b32 v[70:71], 0, 0
	v_pk_mov_b32 v[72:73], 0, 0
	ds_read_b128 v[196:199], v146 offset:1024
	v_pk_mov_b32 v[74:75], 0, 0
	v_pk_mov_b32 v[76:77], 0, 0
	v_pk_mov_b32 v[78:79], 0, 0
	v_pk_mov_b32 v[80:81], 0, 0
	ds_read_b128 v[200:203], v146 offset:2048
	v_pk_mov_b32 v[82:83], 0, 0
	v_pk_mov_b32 v[84:85], 0, 0
	v_pk_mov_b32 v[86:87], 0, 0
	v_pk_mov_b32 v[88:89], 0, 0
	ds_read_b128 v[204:207], v146 offset:3072
	v_pk_mov_b32 v[90:91], 0, 0
	v_pk_mov_b32 v[92:93], 0, 0
	v_pk_mov_b32 v[94:95], 0, 0
	v_pk_mov_b32 v[96:97], 0, 0
	ds_read_b128 v[208:211], v146 offset:4096
	v_pk_mov_b32 v[98:99], 0, 0
	v_pk_mov_b32 v[100:101], 0, 0
	v_pk_mov_b32 v[102:103], 0, 0
	v_pk_mov_b32 v[104:105], 0, 0
	ds_read_b128 v[212:215], v146 offset:5120
	v_pk_mov_b32 v[106:107], 0, 0
	v_pk_mov_b32 v[108:109], 0, 0
	v_pk_mov_b32 v[110:111], 0, 0
	v_pk_mov_b32 v[112:113], 0, 0
	ds_read_b128 v[216:219], v146 offset:6144
	v_pk_mov_b32 v[114:115], 0, 0
	v_pk_mov_b32 v[116:117], 0, 0
	v_pk_mov_b32 v[118:119], 0, 0
	v_pk_mov_b32 v[120:121], 0, 0
	ds_read_b128 v[220:223], v146 offset:7168
	v_pk_mov_b32 v[122:123], 0, 0
	v_pk_mov_b32 v[124:125], 0, 0
	v_pk_mov_b32 v[126:127], 0, 0
	v_pk_mov_b32 v[128:129], 0, 0
	global_load_lds_dwordx4 v[142:143], off
	v_lshl_add_u64 v[142:143], s[24:25], 0, v[140:141]
	s_add_i32 m0, s45, 0xe000
	s_nop 0
	global_load_lds_dwordx4 v[142:143], off
	s_waitcnt vmcnt(8)
	s_waitcnt lgkmcnt(0)
	s_barrier
	s_branch .Lpeel_766

; #define PG8_STAGE(bufoff, gbase, voff) do { _Pragma("unroll") for (int _i = 0; _i < 2; ++_i) \
;         __builtin_amdgcn_global_load_lds((const unsigned*)((const char*)(gbase) + (voff)[_i]), (PG8_LAS unsigned*)(lds + (bufoff) + ldsw + _i * 8192), 16, 0, 0); } while (0)
; #define PG8_LDA(dst, b, h) do { _Pragma("unroll") for (int m = 0; m < 4; ++m) _Pragma("unroll") for (int k = 0; k < 2; ++k) dst[m][k] = *(const PG8_LAS bf16x8*)(lds + PG8_SA(b, h) + aoff + m * 2048 + k * 1024); } while (0)
; #define PG8_LDB(dst, b, h) do { _Pragma("unroll") for (int n = 0; n < 2; ++n) _Pragma("unroll") for (int k = 0; k < 2; ++k) dst[n][k] = *(const PG8_LAS bf16x8*)(lds + PG8_SB(b, h) + boff + n * 2048 + k * 1024); } while (0)
; #define PG8_WAIT_V(n) asm volatile("s_waitcnt vmcnt(" #n ")" ::: "memory")
; #define PG8_WAIT_L(n) asm volatile("s_waitcnt lgkmcnt(" #n ")" ::: "memory")
; template <class Epi, class Sched, bool ALIGN_EPI = false, bool SP2 = false, bool ABLK = false, bool BBLK = false>
; __device__ __forceinline__ void gemm_phase(PG8_LAS unsigned char* lds, const Gemm g, const Sched& S, const Epi& E) {
;     ...
;         const char* nA = has_next ? (const char*)g.A + (size_t)nxt.pm * tstepA : cA; const char* nB = has_next ? (const char*)g.Bt + (size_t)nxt.pn * tstepB : cB;
;         for (int t = 0; t < nt; t += 2) {
;             const bool last = (t == nt - 2);
;             const char* a1 = cA + (size_t)(t + 1) * kstepA;
;             const char* a2 = last ? nA : cA + (size_t)(t + 2) * kstepA; const char* b2 = last ? nB : cB + (size_t)(t + 2) * kstepB;
;             const char* a3 = a2 + kstepA; const char* b3 = b2 + kstepB;
;             if (last && has_next) S.a_ready(nxt);
;             if constexpr (SP2) {
;             PG8_LDB(B0, 0, 0); PG8_LDB(B1, 0, 1); PG8_SCHED; PG8_LDA(At, 0, 0); PG8_STAGE(PG8_SA(1, 1), a1 + hstepA, voffA);
;             PG8_WAIT_V(8); PG8_WAIT_L(0); PG8_BAR; PG8_MMA(0, 0, At, B0); PG8_MMA(0, 1, At, B1); PG8_BAR; PG8_SCHED;
;     ...
; #pragma unroll
;         for (int a = 0; a < 2; ++a)
; #pragma unroll
;             for (int b = 0; b < 2; ++b)
; #pragma unroll
;                 for (int m = 0; m < 4; ++m)
; #pragma unroll
;                     for (int n = 0; n < 2; ++n) acc[a][b][m][n] = (f32x4){0.f, 0.f, 0.f, 0.f};
;         cur = nxt; cA = nA; cB = nB; ++ui;
;         if constexpr (ALIGN_EPI) { if (wr == 1) PG8_BAR; }
.LBB0_789:
	s_ashr_i32 s15, s14, 31
	s_lshl_b64 s[18:19], s[14:15], 20
	s_add_u32 s18, s36, s18
	s_addc_u32 s19, s37, s19
	s_and_b64 s[20:21], s[6:7], exec
	s_cselect_b32 s1, s19, s25
	s_cselect_b32 s11, s18, s24
	s_ashr_i32 s13, s12, 31
	s_lshl_b64 s[20:21], s[12:13], 20
	s_add_u32 s20, s44, s20
	s_addc_u32 s21, s45, s21
	s_and_b64 s[28:29], s[6:7], exec
	s_cselect_b32 s13, s21, s27
	s_cselect_b32 s15, s20, s26
	s_add_u32 s24, s24, 0x80080
	s_addc_u32 s25, s25, 0
	s_add_u32 s23, s26, 0x100
	v_mov_b32_e32 v2, 0
	s_addc_u32 s73, s27, 0
	s_mov_b32 s81, -2
	s_and_b64 vcc, exec, s[8:9]
	s_cbranch_vccnz .Lrb_dft1
	s_barrier
.Lrb_dft1:
	s_add_u32 s26, s24, 0xfff80080
	s_addc_u32 s27, s25, -1
	s_add_i32 s51, 0, 0x10000
	s_cmp_eq_u32 s81, 28
	s_cselect_b32 s29, s1, s27
	s_cselect_b32 s28, s11, s26
	v_add_u32_e32 v142, s51, v145
	s_cselect_b32 s27, s13, s73
	s_cselect_b32 s26, s15, s23
	s_add_i32 s75, 0, 0x14000
	ds_read_b128 v[148:151], v142
	v_pk_mov_b32 v[2:3], 0, 0
	v_pk_mov_b32 v[4:5], 0, 0
	v_pk_mov_b32 v[6:7], 0, 0
	v_pk_mov_b32 v[8:9], 0, 0
	ds_read_b128 v[152:155], v142 offset:1024
	v_pk_mov_b32 v[10:11], 0, 0
	v_pk_mov_b32 v[12:13], 0, 0
	v_pk_mov_b32 v[14:15], 0, 0
	v_pk_mov_b32 v[16:17], 0, 0
	ds_read_b128 v[156:159], v142 offset:2048
	v_pk_mov_b32 v[18:19], 0, 0
	v_pk_mov_b32 v[20:21], 0, 0
	v_pk_mov_b32 v[22:23], 0, 0
	v_pk_mov_b32 v[24:25], 0, 0
	ds_read_b128 v[160:163], v142 offset:3072
	v_pk_mov_b32 v[26:27], 0, 0
	v_pk_mov_b32 v[28:29], 0, 0
	v_pk_mov_b32 v[30:31], 0, 0
	v_pk_mov_b32 v[32:33], 0, 0
	v_add_u32_e32 v142, s75, v145
	ds_read_b128 v[164:167], v142
	v_pk_mov_b32 v[34:35], 0, 0
	v_pk_mov_b32 v[36:37], 0, 0
	v_pk_mov_b32 v[38:39], 0, 0
	v_pk_mov_b32 v[40:41], 0, 0
	ds_read_b128 v[168:171], v142 offset:1024
	v_pk_mov_b32 v[42:43], 0, 0
	v_pk_mov_b32 v[44:45], 0, 0
	v_pk_mov_b32 v[46:47], 0, 0
	v_pk_mov_b32 v[48:49], 0, 0
	ds_read_b128 v[172:175], v142 offset:2048
	v_pk_mov_b32 v[50:51], 0, 0
	v_pk_mov_b32 v[52:53], 0, 0
	v_pk_mov_b32 v[54:55], 0, 0
	v_pk_mov_b32 v[56:57], 0, 0
	ds_read_b128 v[176:179], v142 offset:3072
	v_pk_mov_b32 v[58:59], 0, 0
	v_pk_mov_b32 v[60:61], 0, 0
	v_pk_mov_b32 v[62:63], 0, 0
	v_pk_mov_b32 v[64:65], 0, 0
	v_lshl_add_u64 v[142:143], s[24:25], 0, v[138:139]
	s_add_i32 m0, s46, 0xc000
	ds_read_b128 v[180:183], v146
	v_pk_mov_b32 v[66:67], 0, 0
	v_pk_mov_b32 v[68:69], 0, 0
	v_pk_mov_b32 v[70:71], 0, 0
	v_pk_mov_b32 v[72:73], 0, 0
	ds_read_b128 v[196:199], v146 offset:1024
	v_pk_mov_b32 v[74:75], 0, 0
	v_pk_mov_b32 v[76:77], 0, 0
	v_pk_mov_b32 v[78:79], 0, 0
	v_pk_mov_b32 v[80:81], 0, 0
	ds_read_b128 v[200:203], v146 offset:2048
	v_pk_mov_b32 v[82:83], 0, 0
	v_pk_mov_b32 v[84:85], 0, 0
	v_pk_mov_b32 v[86:87], 0, 0
	v_pk_mov_b32 v[88:89], 0, 0
	ds_read_b128 v[204:207], v146 offset:3072
	v_pk_mov_b32 v[90:91], 0, 0
	v_pk_mov_b32 v[92:93], 0, 0
	v_pk_mov_b32 v[94:95], 0, 0
	v_pk_mov_b32 v[96:97], 0, 0
	ds_read_b128 v[208:211], v146 offset:4096
	v_pk_mov_b32 v[98:99], 0, 0
	v_pk_mov_b32 v[100:101], 0, 0
	v_pk_mov_b32 v[102:103], 0, 0
	v_pk_mov_b32 v[104:105], 0, 0
	ds_read_b128 v[212:215], v146 offset:5120
	v_pk_mov_b32 v[106:107], 0, 0
	v_pk_mov_b32 v[108:109], 0, 0
	v_pk_mov_b32 v[110:111], 0, 0
	v_pk_mov_b32 v[112:113], 0, 0
	ds_read_b128 v[216:219], v146 offset:6144
	v_pk_mov_b32 v[114:115], 0, 0
	v_pk_mov_b32 v[116:117], 0, 0
	v_pk_mov_b32 v[118:119], 0, 0
	v_pk_mov_b32 v[120:121], 0, 0
	ds_read_b128 v[220:223], v146 offset:7168
	v_pk_mov_b32 v[122:123], 0, 0
	v_pk_mov_b32 v[124:125], 0, 0
	v_pk_mov_b32 v[126:127], 0, 0
	v_pk_mov_b32 v[128:129], 0, 0
	global_load_lds_dwordx4 v[142:143], off
	v_lshl_add_u64 v[142:143], s[24:25], 0, v[140:141]
	s_add_i32 m0, s46, 0xe000
	s_nop 0
	global_load_lds_dwordx4 v[142:143], off
	s_waitcnt vmcnt(8)
	s_waitcnt lgkmcnt(0)
	s_barrier
	s_branch .Lpeel_790

; #define PG8_STAGE(bufoff, gbase, voff) do { _Pragma("unroll") for (int _i = 0; _i < 2; ++_i) \
;         __builtin_amdgcn_global_load_lds((const unsigned*)((const char*)(gbase) + (voff)[_i]), (PG8_LAS unsigned*)(lds + (bufoff) + ldsw + _i * 8192), 16, 0, 0); } while (0)
; #define PG8_LDA(dst, b, h) do { _Pragma("unroll") for (int m = 0; m < 4; ++m) _Pragma("unroll") for (int k = 0; k < 2; ++k) dst[m][k] = *(const PG8_LAS bf16x8*)(lds + PG8_SA(b, h) + aoff + m * 2048 + k * 1024); } while (0)
; #define PG8_LDB(dst, b, h) do { _Pragma("unroll") for (int n = 0; n < 2; ++n) _Pragma("unroll") for (int k = 0; k < 2; ++k) dst[n][k] = *(const PG8_LAS bf16x8*)(lds + PG8_SB(b, h) + boff + n * 2048 + k * 1024); } while (0)
; #define PG8_WAIT_V(n) asm volatile("s_waitcnt vmcnt(" #n ")" ::: "memory")
; #define PG8_WAIT_L(n) asm volatile("s_waitcnt lgkmcnt(" #n ")" ::: "memory")
; template <class Epi, class Sched, bool ALIGN_EPI = false, bool SP2 = false, bool ABLK = false, bool BBLK = false>
; __device__ __forceinline__ void gemm_phase(PG8_LAS unsigned char* lds, const Gemm g, const Sched& S, const Epi& E) {
;     ...
;         const char* nA = has_next ? (const char*)g.A + (size_t)nxt.pm * tstepA : cA; const char* nB = has_next ? (const char*)g.Bt + (size_t)nxt.pn * tstepB : cB;
;         for (int t = 0; t < nt; t += 2) {
;             const bool last = (t == nt - 2);
;             const char* a1 = cA + (size_t)(t + 1) * kstepA;
;             const char* a2 = last ? nA : cA + (size_t)(t + 2) * kstepA; const char* b2 = last ? nB : cB + (size_t)(t + 2) * kstepB;
;             const char* a3 = a2 + kstepA; const char* b3 = b2 + kstepB;
;             if (last && has_next) S.a_ready(nxt);
;             if constexpr (SP2) {
;             PG8_LDB(B0, 0, 0); PG8_LDB(B1, 0, 1); PG8_SCHED; PG8_LDA(At, 0, 0); PG8_STAGE(PG8_SA(1, 1), a1 + hstepA, voffA);
;             PG8_WAIT_V(8); PG8_WAIT_L(0); PG8_BAR; PG8_MMA(0, 0, At, B0); PG8_MMA(0, 1, At, B1); PG8_BAR; PG8_SCHED;
;     ...
; #pragma unroll
;         for (int a = 0; a < 2; ++a)
; #pragma unroll
;             for (int b = 0; b < 2; ++b)
; #pragma unroll
;                 for (int m = 0; m < 4; ++m)
; #pragma unroll
;                     for (int n = 0; n < 2; ++n) acc[a][b][m][n] = (f32x4){0.f, 0.f, 0.f, 0.f};
;         cur = nxt; cA = nA; cB = nB; ++ui;
;         if constexpr (ALIGN_EPI) { if (wr == 1) PG8_BAR; }
.LBB0_1116:
	s_ashr_i32 s23, s22, 31
	s_lshl_b64 s[24:25], s[22:23], 18
	s_add_u32 s24, s33, s24
	s_addc_u32 s25, s44, s25
	s_and_b64 s[26:27], s[6:7], exec
	s_cselect_b32 s23, s25, s35
	s_cselect_b32 s31, s24, s34
	s_ashr_i32 s21, s20, 31
	s_lshl_b64 s[26:27], s[20:21], 18
	s_add_u32 s26, s45, s26
	s_addc_u32 s27, s46, s27
	s_and_b64 s[36:37], s[6:7], exec
	s_cselect_b32 s21, s27, s1
	s_cselect_b32 s91, s26, s0
	s_add_u32 s92, s0, 0x10000
	s_addc_u32 s93, s1, 0
	s_add_u32 s0, s34, 0x20080
	v_mov_b32_e32 v2, 0
	s_addc_u32 s1, s35, 0
	s_mov_b32 s94, -2
	s_and_b64 vcc, exec, s[18:19]
	s_cbranch_vccnz .Lrb_m1
	s_barrier
.Lrb_m1:
	s_add_u32 s34, s0, 0xfffe0080
	s_addc_u32 s35, s1, -1
	s_add_i32 s52, 0, 0x10000
	s_cmp_eq_u32 s94, 4
	s_cselect_b32 s37, s23, s35
	s_cselect_b32 s36, s31, s34
	s_cselect_b32 s35, s21, s93
	s_cselect_b32 s34, s91, s92
	s_add_i32 s75, 0, 0x14000
	v_add_u32_e32 v142, s52, v163
	v_add_u32_e32 v160, s75, v163
	ds_read_b128 v[130:133], v142
	v_pk_mov_b32 v[2:3], 0, 0
	v_pk_mov_b32 v[4:5], 0, 0
	v_pk_mov_b32 v[6:7], 0, 0
	v_pk_mov_b32 v[8:9], 0, 0
	ds_read_b128 v[134:137], v142 offset:1024
	v_pk_mov_b32 v[10:11], 0, 0
	v_pk_mov_b32 v[12:13], 0, 0
	v_pk_mov_b32 v[14:15], 0, 0
	v_pk_mov_b32 v[16:17], 0, 0
	ds_read_b128 v[138:141], v142 offset:2048
	v_pk_mov_b32 v[18:19], 0, 0
	v_pk_mov_b32 v[20:21], 0, 0
	v_pk_mov_b32 v[22:23], 0, 0
	v_pk_mov_b32 v[24:25], 0, 0
	ds_read_b128 v[142:145], v142 offset:3072
	v_pk_mov_b32 v[26:27], 0, 0
	v_pk_mov_b32 v[28:29], 0, 0
	v_pk_mov_b32 v[30:31], 0, 0
	v_pk_mov_b32 v[32:33], 0, 0
	ds_read_b128 v[146:149], v160
	v_pk_mov_b32 v[34:35], 0, 0
	v_pk_mov_b32 v[36:37], 0, 0
	v_pk_mov_b32 v[38:39], 0, 0
	v_pk_mov_b32 v[40:41], 0, 0
	ds_read_b128 v[166:169], v160 offset:1024
	v_pk_mov_b32 v[42:43], 0, 0
	v_pk_mov_b32 v[44:45], 0, 0
	v_pk_mov_b32 v[46:47], 0, 0
	v_pk_mov_b32 v[48:49], 0, 0
	ds_read_b128 v[170:173], v160 offset:2048
	v_pk_mov_b32 v[50:51], 0, 0
	v_pk_mov_b32 v[52:53], 0, 0
	v_pk_mov_b32 v[54:55], 0, 0
	v_pk_mov_b32 v[56:57], 0, 0
	ds_read_b128 v[174:177], v160 offset:3072
	v_pk_mov_b32 v[58:59], 0, 0
	v_pk_mov_b32 v[60:61], 0, 0
	v_pk_mov_b32 v[62:63], 0, 0
	v_pk_mov_b32 v[64:65], 0, 0
	v_lshl_add_u64 v[160:161], s[0:1], 0, v[156:157]
	s_add_i32 m0, s29, 0xc000
	ds_read_b128 v[178:181], v165
	v_pk_mov_b32 v[66:67], 0, 0
	v_pk_mov_b32 v[68:69], 0, 0
	v_pk_mov_b32 v[70:71], 0, 0
	v_pk_mov_b32 v[72:73], 0, 0
	ds_read_b128 v[182:185], v165 offset:1024
	v_pk_mov_b32 v[74:75], 0, 0
	v_pk_mov_b32 v[76:77], 0, 0
	v_pk_mov_b32 v[78:79], 0, 0
	v_pk_mov_b32 v[80:81], 0, 0
	ds_read_b128 v[196:199], v165 offset:2048
	v_pk_mov_b32 v[82:83], 0, 0
	v_pk_mov_b32 v[84:85], 0, 0
	v_pk_mov_b32 v[86:87], 0, 0
	v_pk_mov_b32 v[88:89], 0, 0
	ds_read_b128 v[200:203], v165 offset:3072
	v_pk_mov_b32 v[90:91], 0, 0
	v_pk_mov_b32 v[92:93], 0, 0
	v_pk_mov_b32 v[94:95], 0, 0
	v_pk_mov_b32 v[96:97], 0, 0
	ds_read_b128 v[204:207], v165 offset:4096
	v_pk_mov_b32 v[98:99], 0, 0
	v_pk_mov_b32 v[100:101], 0, 0
	v_pk_mov_b32 v[102:103], 0, 0
	v_pk_mov_b32 v[104:105], 0, 0
	ds_read_b128 v[208:211], v165 offset:5120
	v_pk_mov_b32 v[106:107], 0, 0
	v_pk_mov_b32 v[108:109], 0, 0
	v_pk_mov_b32 v[110:111], 0, 0
	v_pk_mov_b32 v[112:113], 0, 0
	ds_read_b128 v[212:215], v165 offset:6144
	v_pk_mov_b32 v[114:115], 0, 0
	v_pk_mov_b32 v[116:117], 0, 0
	v_pk_mov_b32 v[118:119], 0, 0
	v_pk_mov_b32 v[120:121], 0, 0
	ds_read_b128 v[216:219], v165 offset:7168
	v_pk_mov_b32 v[122:123], 0, 0
	v_pk_mov_b32 v[124:125], 0, 0
	v_pk_mov_b32 v[126:127], 0, 0
	v_pk_mov_b32 v[128:129], 0, 0
	global_load_lds_dwordx4 v[160:161], off
	v_lshl_add_u64 v[160:161], s[0:1], 0, v[158:159]
	s_add_i32 m0, s29, 0xe000
	s_nop 0
	global_load_lds_dwordx4 v[160:161], off
	s_waitcnt vmcnt(8)
	s_waitcnt lgkmcnt(0)
	s_barrier
	s_branch .Lpeel_1117

; __device__ __forceinline__ u32x4 pack8(const f32x4 v0, const f32x4 v1) { u32x4 w; w.x = cvt_pk_bf16(v0[0], v0[1]); w.y = cvt_pk_bf16(v0[2], v0[3]); w.z = cvt_pk_bf16(v1[0], v1[1]); w.w = cvt_pk_bf16(v1[2], v1[3]); return w; }
;     __device__ __forceinline__ void operator()(const f32x4 (&acc)[2][2][4][2], const Unit& u, int wr, int wc, int fr_, int fq) const {
;     ...
;         const size_t row0 = (size_t)u.pm * BM + wr * 64 + fr; const int col0 = u.pn * BM + wc * 32 + 8 * fq;
; #pragma unroll
;         for (int ai = 0; ai < 2; ++ai) {
;             u32x4 gw[4][2], ow[4][2];
; #pragma unroll
;             for (int m = 0; m < 4; ++m)
; #pragma unroll
;                 for (int bj = 0; bj < 2; ++bj) { const size_t r = row0 + ai * HALF + m * 16; const int c = col0 + bj * HALF;
;                     gw[m][bj] = *(const u32x4*)(G + r * 6144 + goff + c); if (!FIRST) ow[m][bj] = *(const u32x4*)(Mo + r * DM + c); }
; #pragma unroll
;             for (int m = 0; m < 4; ++m)
; #pragma unroll
;                 for (int bj = 0; bj < 2; ++bj) { const size_t r = row0 + ai * HALF + m * 16; const int c = col0 + bj * HALF;
;                     f32x4 g0, g1; unpack8(gw[m][bj], g0, g1);
;                     f32x4 v0 = g0 * acc[ai][bj][m][0], v1 = g1 * acc[ai][bj][m][1];
;                     if (!FIRST) { f32x4 o0, o1; unpack8(ow[m][bj], o0, o1); v0 += o0; v1 += o1; }
;                     *(u32x4*)((Mdst ? Mdst : Mo) + r * DM + c) = pack8(v0, v1); }
.LBB0_1120:
	s_ashr_i32 s31, s30, 31
	s_lshl_b64 s[0:1], s[30:31], 8
	v_mov_b32_e32 v130, v162
	s_add_u32 s0, s0, s73
	s_addc_u32 s1, s1, s89
	v_ashrrev_i32_e32 v131, 31, v130
	v_lshl_add_u64 v[178:179], s[0:1], 0, v[130:131]
	v_lshl_or_b32 v130, s28, 8, v164
	v_mov_b64_e32 v[132:133], s[14:15]
	s_movk_i32 s21, 0x3000
	v_ashrrev_i32_e32 v131, 31, v130
	v_mad_u64_u32 v[132:133], s[0:1], v178, s21, v[132:133]
	v_mad_i32_i24 v133, v179, s21, v133
	v_lshlrev_b64 v[180:181], 1, v[130:131]
	v_lshl_add_u64 v[160:161], v[132:133], 0, v[180:181]
	global_load_dwordx4 v[166:169], v[160:161], off
	global_load_dwordx4 v[170:173], v[160:161], off offset:256
	s_mov_b32 s91, 0x30000
	v_add_co_u32_e32 v132, vcc, s91, v160
	s_mov_b64 s[34:35], 0x30000
	s_nop 0
	v_addc_co_u32_e32 v133, vcc, 0, v161, vcc
	v_lshl_add_u64 v[130:131], v[160:161], 0, s[34:35]
	global_load_dwordx4 v[174:177], v[132:133], off
	global_load_dwordx4 v[146:149], v[130:131], off offset:256
	s_mov_b32 s94, 0x60000
	v_add_co_u32_e32 v132, vcc, s94, v160
	s_mov_b64 s[0:1], 0x60000
	s_nop 0
	v_addc_co_u32_e32 v133, vcc, 0, v161, vcc
	v_lshl_add_u64 v[130:131], v[160:161], 0, s[0:1]
	global_load_dwordx4 v[142:145], v[132:133], off
	global_load_dwordx4 v[138:141], v[130:131], off offset:256
	s_mov_b32 s0, 0x90000
	s_mov_b64 s[36:37], 0x90000
	v_add_co_u32_e32 v132, vcc, s0, v160
	v_lshl_add_u64 v[130:131], v[160:161], 0, s[36:37]
	s_nop 0
	v_addc_co_u32_e32 v133, vcc, 0, v161, vcc
	global_load_dwordx4 v[134:137], v[132:133], off
	s_nop 0
	global_load_dwordx4 v[130:133], v[130:131], off offset:256
	v_add_co_u32_e32 v188, vcc, 0x180000, v160
	s_nop 1
	v_addc_co_u32_e32 v189, vcc, 0, v161, vcc
	s_nop 0
	global_load_dwordx4 v[204:207], v[188:189], off
	global_load_dwordx4 v[208:211], v[188:189], off offset:256
	v_add_co_u32_e32 v188, vcc, 0x1b0000, v160
	s_nop 1
	v_addc_co_u32_e32 v189, vcc, 0, v161, vcc
	s_nop 0
	global_load_dwordx4 v[212:215], v[188:189], off
	global_load_dwordx4 v[216:219], v[188:189], off offset:256
	v_add_co_u32_e32 v188, vcc, 0x1e0000, v160
	s_nop 1
	v_addc_co_u32_e32 v189, vcc, 0, v161, vcc
	s_nop 0
	global_load_dwordx4 v[220:223], v[188:189], off
	global_load_dwordx4 v[224:227], v[188:189], off offset:256
	v_add_co_u32_e32 v188, vcc, 0x210000, v160
	s_nop 1
	v_addc_co_u32_e32 v189, vcc, 0, v161, vcc
	s_nop 0
	global_load_dwordx4 v[200:203], v[188:189], off
	global_load_dwordx4 v[196:199], v[188:189], off offset:256
	v_lshlrev_b64 v[178:179], 12, v[178:179]
	s_mov_b64 s[30:31], 0x20000
	s_mov_b32 s1, 0x180000
	s_mov_b32 s52, 0x80000
	s_waitcnt vmcnt(8)
	v_lshlrev_b32_e32 v182, 16, v166
	v_and_b32_e32 v183, 0xffff0000, v166
	v_lshlrev_b32_e32 v184, 16, v168
	v_and_b32_e32 v185, 0xffff0000, v168
	v_lshlrev_b32_e32 v166, 16, v167
	v_and_b32_e32 v167, 0xffff0000, v167
	v_lshlrev_b32_e32 v168, 16, v169
	v_and_b32_e32 v169, 0xffff0000, v169
	v_pk_mul_f32 v[126:127], v[126:127], v[182:183]
	v_pk_mul_f32 v[122:123], v[122:123], v[184:185]
	v_pk_mul_f32 v[128:129], v[128:129], v[166:167]
	v_pk_mul_f32 v[166:167], v[124:125], v[168:169]
	v_cvt_pk_bf16_f32 v124, v126, v127
	v_cvt_pk_bf16_f32 v125, v128, v129
	v_cvt_pk_bf16_f32 v126, v122, v123
	v_lshl_add_u64 v[122:123], s[2:3], 0, v[178:179]
	v_lshl_add_u64 v[122:123], v[122:123], 0, v[180:181]
	v_cvt_pk_bf16_f32 v127, v166, v167
	global_store_dwordx4 v[122:123], v[124:127], off
	v_lshlrev_b32_e32 v128, 16, v172
	v_and_b32_e32 v129, 0xffff0000, v172
	v_lshlrev_b32_e32 v124, 16, v170
	v_and_b32_e32 v125, 0xffff0000, v170
	v_lshlrev_b32_e32 v166, 16, v173
	v_and_b32_e32 v167, 0xffff0000, v173
	v_lshlrev_b32_e32 v126, 16, v171
	v_and_b32_e32 v127, 0xffff0000, v171
	v_pk_mul_f32 v[110:111], v[110:111], v[124:125]
	v_pk_mul_f32 v[124:125], v[108:109], v[166:167]
	v_pk_mul_f32 v[108:109], v[106:107], v[128:129]
	v_pk_mul_f32 v[112:113], v[112:113], v[126:127]
	v_cvt_pk_bf16_f32 v106, v110, v111
	v_lshlrev_b32_e32 v110, 16, v176
	v_cvt_pk_bf16_f32 v107, v112, v113
	v_cvt_pk_bf16_f32 v108, v108, v109
	v_cvt_pk_bf16_f32 v109, v124, v125
	global_store_dwordx4 v[122:123], v[106:109], off offset:256
	v_lshlrev_b32_e32 v112, 16, v177
	v_and_b32_e32 v113, 0xffff0000, v177
	v_lshlrev_b32_e32 v106, 16, v174
	v_and_b32_e32 v107, 0xffff0000, v174
	v_lshlrev_b32_e32 v108, 16, v175
	v_and_b32_e32 v109, 0xffff0000, v175
	v_and_b32_e32 v111, 0xffff0000, v176
	v_pk_mul_f32 v[108:109], v[120:121], v[108:109]
	v_pk_mul_f32 v[106:107], v[118:119], v[106:107]
	v_pk_mul_f32 v[112:113], v[116:117], v[112:113]
	v_pk_mul_f32 v[110:111], v[114:115], v[110:111]
	v_cvt_pk_bf16_f32 v106, v106, v107
	v_cvt_pk_bf16_f32 v107, v108, v109
	v_lshlrev_b32_e32 v114, 16, v149
	v_cvt_pk_bf16_f32 v108, v110, v111
	v_cvt_pk_bf16_f32 v109, v112, v113
	v_add_co_u32_e32 v112, vcc, s80, v122
	v_and_b32_e32 v115, 0xffff0000, v149
	s_nop 0
	v_addc_co_u32_e32 v113, vcc, 0, v123, vcc
	global_store_dwordx4 v[112:113], v[106:109], off
	v_lshlrev_b32_e32 v112, 16, v148
	v_and_b32_e32 v113, 0xffff0000, v148
	v_lshlrev_b32_e32 v106, 16, v146
	v_and_b32_e32 v107, 0xffff0000, v146
	v_lshlrev_b32_e32 v108, 16, v147
	v_and_b32_e32 v109, 0xffff0000, v147
	v_pk_mul_f32 v[102:103], v[102:103], v[106:107]
	v_pk_mul_f32 v[106:107], v[100:101], v[114:115]
	v_pk_mul_f32 v[100:101], v[98:99], v[112:113]
	v_lshl_add_u64 v[110:111], v[122:123], 0, s[48:49]
	v_pk_mul_f32 v[104:105], v[104:105], v[108:109]
	v_cvt_pk_bf16_f32 v98, v102, v103
	v_lshlrev_b32_e32 v102, 16, v144
	v_cvt_pk_bf16_f32 v99, v104, v105
	v_cvt_pk_bf16_f32 v100, v100, v101
	v_cvt_pk_bf16_f32 v101, v106, v107
	global_store_dwordx4 v[110:111], v[98:101], off offset:256
	v_and_b32_e32 v103, 0xffff0000, v144
	v_lshlrev_b32_e32 v104, 16, v145
; __device__ __forceinline__ u32x4 pack8(const f32x4 v0, const f32x4 v1) { u32x4 w; w.x = cvt_pk_bf16(v0[0], v0[1]); w.y = cvt_pk_bf16(v0[2], v0[3]); w.z = cvt_pk_bf16(v1[0], v1[1]); w.w = cvt_pk_bf16(v1[2], v1[3]); return w; }
;     __device__ __forceinline__ void operator()(const f32x4 (&acc)[2][2][4][2], const Unit& u, int wr, int wc, int fr_, int fq) const {
;     ...
;             for (int m = 0; m < 4; ++m)
; #pragma unroll
;                 for (int bj = 0; bj < 2; ++bj) { const size_t r = row0 + ai * HALF + m * 16; const int c = col0 + bj * HALF;
;                     f32x4 g0, g1; unpack8(gw[m][bj], g0, g1);
;                     f32x4 v0 = g0 * acc[ai][bj][m][0], v1 = g1 * acc[ai][bj][m][1];
;                     if (!FIRST) { f32x4 o0, o1; unpack8(ow[m][bj], o0, o1); v0 += o0; v1 += o1; }
;                     *(u32x4*)((Mdst ? Mdst : Mo) + r * DM + c) = pack8(v0, v1); }
	v_lshlrev_b32_e32 v100, 16, v143
	v_and_b32_e32 v101, 0xffff0000, v143
	v_lshlrev_b32_e32 v98, 16, v142
	v_and_b32_e32 v99, 0xffff0000, v142
	v_and_b32_e32 v105, 0xffff0000, v145
	v_pk_mul_f32 v[96:97], v[96:97], v[100:101]
	v_pk_mul_f32 v[94:95], v[94:95], v[98:99]
	v_pk_mul_f32 v[98:99], v[92:93], v[104:105]
	v_pk_mul_f32 v[92:93], v[90:91], v[102:103]
	v_cvt_pk_bf16_f32 v90, v94, v95
	v_cvt_pk_bf16_f32 v91, v96, v97
	v_add_co_u32_e32 v96, vcc, s95, v122
	v_cvt_pk_bf16_f32 v92, v92, v93
	v_cvt_pk_bf16_f32 v93, v98, v99
	v_lshlrev_b32_e32 v98, 16, v141
	s_nop 0
	v_addc_co_u32_e32 v97, vcc, 0, v123, vcc
	global_store_dwordx4 v[96:97], v[90:93], off
	v_lshlrev_b32_e32 v96, 16, v140
	v_and_b32_e32 v97, 0xffff0000, v140
	v_lshlrev_b32_e32 v90, 16, v138
	v_and_b32_e32 v91, 0xffff0000, v138
	v_and_b32_e32 v99, 0xffff0000, v141
	v_lshlrev_b32_e32 v92, 16, v139
	v_and_b32_e32 v93, 0xffff0000, v139
	v_pk_mul_f32 v[86:87], v[86:87], v[90:91]
	v_pk_mul_f32 v[90:91], v[84:85], v[98:99]
	v_pk_mul_f32 v[84:85], v[82:83], v[96:97]
	v_lshl_add_u64 v[94:95], v[122:123], 0, s[30:31]
	v_pk_mul_f32 v[88:89], v[88:89], v[92:93]
	v_cvt_pk_bf16_f32 v82, v86, v87
	v_lshlrev_b32_e32 v86, 16, v136
	v_cvt_pk_bf16_f32 v83, v88, v89
	v_cvt_pk_bf16_f32 v84, v84, v85
	v_cvt_pk_bf16_f32 v85, v90, v91
	global_store_dwordx4 v[94:95], v[82:85], off offset:256
	v_and_b32_e32 v87, 0xffff0000, v136
	v_lshlrev_b32_e32 v88, 16, v137
	v_lshlrev_b32_e32 v84, 16, v135
	v_and_b32_e32 v85, 0xffff0000, v135
	v_lshlrev_b32_e32 v82, 16, v134
	v_and_b32_e32 v83, 0xffff0000, v134
	v_and_b32_e32 v89, 0xffff0000, v137
	v_pk_mul_f32 v[80:81], v[80:81], v[84:85]
	v_pk_mul_f32 v[78:79], v[78:79], v[82:83]
	v_pk_mul_f32 v[82:83], v[76:77], v[88:89]
	v_pk_mul_f32 v[76:77], v[74:75], v[86:87]
	v_cvt_pk_bf16_f32 v74, v78, v79
	v_cvt_pk_bf16_f32 v75, v80, v81
	v_add_co_u32_e32 v80, vcc, s91, v122
	v_cvt_pk_bf16_f32 v76, v76, v77
	v_cvt_pk_bf16_f32 v77, v82, v83
	v_lshlrev_b32_e32 v82, 16, v133
	s_nop 0
	v_addc_co_u32_e32 v81, vcc, 0, v123, vcc
	global_store_dwordx4 v[80:81], v[74:77], off
	v_lshlrev_b32_e32 v80, 16, v132
	v_and_b32_e32 v81, 0xffff0000, v132
	v_lshlrev_b32_e32 v74, 16, v130
	v_and_b32_e32 v75, 0xffff0000, v130
	v_and_b32_e32 v83, 0xffff0000, v133
	v_lshlrev_b32_e32 v76, 16, v131
	v_and_b32_e32 v77, 0xffff0000, v131
	v_pk_mul_f32 v[70:71], v[70:71], v[74:75]
	v_pk_mul_f32 v[74:75], v[68:69], v[82:83]
	v_pk_mul_f32 v[68:69], v[66:67], v[80:81]
	v_lshl_add_u64 v[78:79], v[122:123], 0, s[34:35]
	v_pk_mul_f32 v[72:73], v[72:73], v[76:77]
	v_cvt_pk_bf16_f32 v66, v70, v71
	s_mov_b64 s[30:31], 0x180000
	v_cvt_pk_bf16_f32 v67, v72, v73
	v_cvt_pk_bf16_f32 v68, v68, v69
	v_cvt_pk_bf16_f32 v69, v74, v75
	global_store_dwordx4 v[78:79], v[66:69], off offset:256
	s_nop 1
	s_mov_b64 s[30:31], 0x80000
	s_waitcnt vmcnt(15)
	v_lshlrev_b32_e32 v98, 16, v204
	v_and_b32_e32 v99, 0xffff0000, v204
	v_lshlrev_b32_e32 v204, 16, v205
	v_and_b32_e32 v205, 0xffff0000, v205
	v_lshlrev_b32_e32 v100, 16, v206
	v_and_b32_e32 v101, 0xffff0000, v206
	v_lshlrev_b32_e32 v206, 16, v207
	v_and_b32_e32 v207, 0xffff0000, v207
	v_pk_mul_f32 v[64:65], v[64:65], v[204:205]
	v_pk_mul_f32 v[62:63], v[62:63], v[98:99]
	v_pk_mul_f32 v[204:205], v[60:61], v[206:207]
	v_pk_mul_f32 v[60:61], v[58:59], v[100:101]
	v_cvt_pk_bf16_f32 v58, v62, v63
	v_cvt_pk_bf16_f32 v59, v64, v65
	v_add_co_u32_e32 v64, vcc, s52, v122
	v_cvt_pk_bf16_f32 v60, v60, v61
	v_cvt_pk_bf16_f32 v61, v204, v205
	s_waitcnt vmcnt(14)
	v_lshlrev_b32_e32 v204, 16, v211
	v_addc_co_u32_e32 v65, vcc, 0, v123, vcc
	global_store_dwordx4 v[64:65], v[58:61], off
	v_lshlrev_b32_e32 v64, 16, v210
	v_and_b32_e32 v65, 0xffff0000, v210
	v_lshlrev_b32_e32 v58, 16, v208
	v_and_b32_e32 v59, 0xffff0000, v208
	v_and_b32_e32 v205, 0xffff0000, v211
	v_lshlrev_b32_e32 v60, 16, v209
	v_and_b32_e32 v61, 0xffff0000, v209
	v_pk_mul_f32 v[54:55], v[54:55], v[58:59]
	v_pk_mul_f32 v[58:59], v[52:53], v[204:205]
	v_pk_mul_f32 v[52:53], v[50:51], v[64:65]
	v_lshl_add_u64 v[62:63], v[122:123], 0, s[30:31]
	v_pk_mul_f32 v[56:57], v[56:57], v[60:61]
	v_cvt_pk_bf16_f32 v50, v54, v55
	s_waitcnt vmcnt(14)
; __device__ __forceinline__ u32x4 pack8(const f32x4 v0, const f32x4 v1) { u32x4 w; w.x = cvt_pk_bf16(v0[0], v0[1]); w.y = cvt_pk_bf16(v0[2], v0[3]); w.z = cvt_pk_bf16(v1[0], v1[1]); w.w = cvt_pk_bf16(v1[2], v1[3]); return w; }
; #define PG8_BAR __builtin_amdgcn_s_barrier()
;     __device__ __forceinline__ void operator()(const f32x4 (&acc)[2][2][4][2], const Unit& u, int wr, int wc, int fr_, int fq) const {
;     ...
;             for (int m = 0; m < 4; ++m)
; #pragma unroll
;                 for (int bj = 0; bj < 2; ++bj) { const size_t r = row0 + ai * HALF + m * 16; const int c = col0 + bj * HALF;
;                     f32x4 g0, g1; unpack8(gw[m][bj], g0, g1);
;                     f32x4 v0 = g0 * acc[ai][bj][m][0], v1 = g1 * acc[ai][bj][m][1];
;                     if (!FIRST) { f32x4 o0, o1; unpack8(ow[m][bj], o0, o1); v0 += o0; v1 += o1; }
;                     *(u32x4*)((Mdst ? Mdst : Mo) + r * DM + c) = pack8(v0, v1); }
;             asm volatile("" ::: "memory"); }
; template <class Epi, class Sched, bool ALIGN_EPI = false, bool SP2 = false, bool ABLK = false, bool BBLK = false>
; __device__ __forceinline__ void gemm_phase(PG8_LAS unsigned char* lds, const Gemm g, const Sched& S, const Epi& E) {
;     ...
;         if (!has_next) break;
; #pragma unroll
;         for (int a = 0; a < 2; ++a)
; #pragma unroll
;             for (int b = 0; b < 2; ++b)
; #pragma unroll
;                 for (int m = 0; m < 4; ++m)
; #pragma unroll
;                     for (int n = 0; n < 2; ++n) acc[a][b][m][n] = (f32x4){0.f, 0.f, 0.f, 0.f};
;         cur = nxt; cA = nA; cB = nB; ++ui;
;         if constexpr (ALIGN_EPI) { if (wr == 1) PG8_BAR; }
	v_lshlrev_b32_e32 v54, 16, v214
	v_cvt_pk_bf16_f32 v51, v56, v57
	v_cvt_pk_bf16_f32 v52, v52, v53
	v_cvt_pk_bf16_f32 v53, v58, v59
	global_store_dwordx4 v[62:63], v[50:53], off offset:256
	v_and_b32_e32 v55, 0xffff0000, v214
	v_lshlrev_b32_e32 v56, 16, v215
	v_lshlrev_b32_e32 v52, 16, v213
	v_and_b32_e32 v53, 0xffff0000, v213
	v_lshlrev_b32_e32 v50, 16, v212
	v_and_b32_e32 v51, 0xffff0000, v212
	v_and_b32_e32 v57, 0xffff0000, v215
	v_pk_mul_f32 v[48:49], v[48:49], v[52:53]
	v_pk_mul_f32 v[46:47], v[46:47], v[50:51]
	v_pk_mul_f32 v[50:51], v[44:45], v[56:57]
	v_pk_mul_f32 v[44:45], v[42:43], v[54:55]
	v_cvt_pk_bf16_f32 v42, v46, v47
	v_cvt_pk_bf16_f32 v43, v48, v49
	v_add_co_u32_e32 v48, vcc, s0, v122
	v_cvt_pk_bf16_f32 v44, v44, v45
	v_cvt_pk_bf16_f32 v45, v50, v51
	s_waitcnt vmcnt(14)
	v_lshlrev_b32_e32 v50, 16, v219
	v_addc_co_u32_e32 v49, vcc, 0, v123, vcc
	global_store_dwordx4 v[48:49], v[42:45], off
	v_lshlrev_b32_e32 v48, 16, v218
	v_and_b32_e32 v49, 0xffff0000, v218
	v_lshlrev_b32_e32 v42, 16, v216
	v_and_b32_e32 v43, 0xffff0000, v216
	v_lshlrev_b32_e32 v44, 16, v217
	v_and_b32_e32 v45, 0xffff0000, v217
	v_and_b32_e32 v51, 0xffff0000, v219
	v_lshl_add_u64 v[46:47], v[122:123], 0, s[36:37]
	v_pk_mul_f32 v[40:41], v[40:41], v[44:45]
	v_pk_mul_f32 v[38:39], v[38:39], v[42:43]
	v_pk_mul_f32 v[42:43], v[36:37], v[50:51]
	v_pk_mul_f32 v[36:37], v[34:35], v[48:49]
	v_cvt_pk_bf16_f32 v34, v38, v39
	v_cvt_pk_bf16_f32 v35, v40, v41
	s_waitcnt vmcnt(14)
	v_lshlrev_b32_e32 v38, 16, v222
	v_cvt_pk_bf16_f32 v36, v36, v37
	v_cvt_pk_bf16_f32 v37, v42, v43
	global_store_dwordx4 v[46:47], v[34:37], off offset:256
	v_and_b32_e32 v39, 0xffff0000, v222
	v_lshlrev_b32_e32 v40, 16, v223
	v_lshlrev_b32_e32 v34, 16, v220
	v_and_b32_e32 v35, 0xffff0000, v220
	v_lshlrev_b32_e32 v36, 16, v221
	v_and_b32_e32 v37, 0xffff0000, v221
	v_and_b32_e32 v41, 0xffff0000, v223
	v_pk_mul_f32 v[30:31], v[30:31], v[34:35]
	s_mov_b64 s[0:1], 0xa0000
	v_pk_mul_f32 v[32:33], v[32:33], v[36:37]
	v_pk_mul_f32 v[34:35], v[28:29], v[40:41]
	v_pk_mul_f32 v[28:29], v[26:27], v[38:39]
	v_cvt_pk_bf16_f32 v26, v30, v31
	v_lshl_add_u64 v[30:31], v[122:123], 0, s[0:1]
	s_mov_b32 s0, 0xa0000
	v_cvt_pk_bf16_f32 v27, v32, v33
	v_add_co_u32_e32 v32, vcc, s0, v122
	v_cvt_pk_bf16_f32 v28, v28, v29
	v_cvt_pk_bf16_f32 v29, v34, v35
	s_waitcnt vmcnt(14)
	v_lshlrev_b32_e32 v34, 16, v227
	v_addc_co_u32_e32 v33, vcc, 0, v123, vcc
	global_store_dwordx4 v[32:33], v[26:29], off
	v_lshlrev_b32_e32 v32, 16, v226
	v_and_b32_e32 v33, 0xffff0000, v226
	v_lshlrev_b32_e32 v26, 16, v224
	v_and_b32_e32 v27, 0xffff0000, v224
	v_lshlrev_b32_e32 v28, 16, v225
	v_and_b32_e32 v29, 0xffff0000, v225
	v_and_b32_e32 v35, 0xffff0000, v227
	v_pk_mul_f32 v[24:25], v[24:25], v[28:29]
	v_pk_mul_f32 v[22:23], v[22:23], v[26:27]
	v_pk_mul_f32 v[26:27], v[20:21], v[34:35]
	v_pk_mul_f32 v[20:21], v[18:19], v[32:33]
	v_cvt_pk_bf16_f32 v18, v22, v23
	v_cvt_pk_bf16_f32 v19, v24, v25
	s_waitcnt vmcnt(14)
	v_lshlrev_b32_e32 v22, 16, v202
	v_cvt_pk_bf16_f32 v20, v20, v21
	v_cvt_pk_bf16_f32 v21, v26, v27
	global_store_dwordx4 v[30:31], v[18:21], off offset:256
	v_and_b32_e32 v23, 0xffff0000, v202
	v_lshlrev_b32_e32 v24, 16, v203
	v_lshlrev_b32_e32 v18, 16, v200
	v_and_b32_e32 v19, 0xffff0000, v200
	v_lshlrev_b32_e32 v20, 16, v201
	v_and_b32_e32 v21, 0xffff0000, v201
	v_and_b32_e32 v25, 0xffff0000, v203
	v_pk_mul_f32 v[14:15], v[14:15], v[18:19]
	s_mov_b64 s[0:1], 0xb0000
	v_pk_mul_f32 v[16:17], v[16:17], v[20:21]
	v_pk_mul_f32 v[18:19], v[12:13], v[24:25]
	v_pk_mul_f32 v[12:13], v[10:11], v[22:23]
	v_cvt_pk_bf16_f32 v10, v14, v15
	v_lshl_add_u64 v[14:15], v[122:123], 0, s[0:1]
	s_mov_b32 s0, 0xb0000
	v_cvt_pk_bf16_f32 v11, v16, v17
	v_add_co_u32_e32 v16, vcc, s0, v122
	v_cvt_pk_bf16_f32 v12, v12, v13
	v_cvt_pk_bf16_f32 v13, v18, v19
	s_waitcnt vmcnt(14)
	v_lshlrev_b32_e32 v18, 16, v199
	v_addc_co_u32_e32 v17, vcc, 0, v123, vcc
	global_store_dwordx4 v[16:17], v[10:13], off
	v_lshlrev_b32_e32 v16, 16, v198
	v_and_b32_e32 v17, 0xffff0000, v198
	v_lshlrev_b32_e32 v10, 16, v196
	v_and_b32_e32 v11, 0xffff0000, v196
	v_and_b32_e32 v19, 0xffff0000, v199
	v_lshlrev_b32_e32 v12, 16, v197
	v_and_b32_e32 v13, 0xffff0000, v197
	v_pk_mul_f32 v[6:7], v[6:7], v[10:11]
	v_pk_mul_f32 v[10:11], v[4:5], v[18:19]
	v_pk_mul_f32 v[4:5], v[2:3], v[16:17]
	v_pk_mul_f32 v[8:9], v[8:9], v[12:13]
	v_cvt_pk_bf16_f32 v2, v6, v7
	s_mov_b64 s[0:1], -1
	v_cvt_pk_bf16_f32 v3, v8, v9
	v_cvt_pk_bf16_f32 v4, v4, v5
	v_cvt_pk_bf16_f32 v5, v10, v11
	global_store_dwordx4 v[14:15], v[2:5], off offset:256
	s_andn2_b64 vcc, exec, s[6:7]
	s_cbranch_vccnz .LBB0_1110
	s_andn2_b64 vcc, exec, s[12:13]
	s_cbranch_vccnz .LBB0_1109
	s_branch .LBB0_1109

; #define PG8_STAGE(bufoff, gbase, voff) do { _Pragma("unroll") for (int _i = 0; _i < 2; ++_i) \
;         __builtin_amdgcn_global_load_lds((const unsigned*)((const char*)(gbase) + (voff)[_i]), (PG8_LAS unsigned*)(lds + (bufoff) + ldsw + _i * 8192), 16, 0, 0); } while (0)
; #define PG8_LDA(dst, b, h) do { _Pragma("unroll") for (int m = 0; m < 4; ++m) _Pragma("unroll") for (int k = 0; k < 2; ++k) dst[m][k] = *(const PG8_LAS bf16x8*)(lds + PG8_SA(b, h) + aoff + m * 2048 + k * 1024); } while (0)
; #define PG8_LDB(dst, b, h) do { _Pragma("unroll") for (int n = 0; n < 2; ++n) _Pragma("unroll") for (int k = 0; k < 2; ++k) dst[n][k] = *(const PG8_LAS bf16x8*)(lds + PG8_SB(b, h) + boff + n * 2048 + k * 1024); } while (0)
; #define PG8_WAIT_V(n) asm volatile("s_waitcnt vmcnt(" #n ")" ::: "memory")
; #define PG8_WAIT_L(n) asm volatile("s_waitcnt lgkmcnt(" #n ")" ::: "memory")
; template <class Epi, class Sched, bool ALIGN_EPI = false, bool SP2 = false, bool ABLK = false, bool BBLK = false>
; __device__ __forceinline__ void gemm_phase(PG8_LAS unsigned char* lds, const Gemm g, const Sched& S, const Epi& E) {
;     ...
;         const char* nA = has_next ? (const char*)g.A + (size_t)nxt.pm * tstepA : cA; const char* nB = has_next ? (const char*)g.Bt + (size_t)nxt.pn * tstepB : cB;
;         for (int t = 0; t < nt; t += 2) {
;             const bool last = (t == nt - 2);
;             const char* a1 = cA + (size_t)(t + 1) * kstepA;
;             const char* a2 = last ? nA : cA + (size_t)(t + 2) * kstepA; const char* b2 = last ? nB : cB + (size_t)(t + 2) * kstepB;
;             const char* a3 = a2 + kstepA; const char* b3 = b2 + kstepB;
;             if (last && has_next) S.a_ready(nxt);
;             if constexpr (SP2) {
;             PG8_LDB(B0, 0, 0); PG8_LDB(B1, 0, 1); PG8_SCHED; PG8_LDA(At, 0, 0); PG8_STAGE(PG8_SA(1, 1), a1 + hstepA, voffA);
;             PG8_WAIT_V(8); PG8_WAIT_L(0); PG8_BAR; PG8_MMA(0, 0, At, B0); PG8_MMA(0, 1, At, B1); PG8_BAR; PG8_SCHED;
;     ...
; #pragma unroll
;         for (int a = 0; a < 2; ++a)
; #pragma unroll
;             for (int b = 0; b < 2; ++b)
; #pragma unroll
;                 for (int m = 0; m < 4; ++m)
; #pragma unroll
;                     for (int n = 0; n < 2; ++n) acc[a][b][m][n] = (f32x4){0.f, 0.f, 0.f, 0.f};
;         cur = nxt; cA = nA; cB = nB; ++ui;
;         if constexpr (ALIGN_EPI) { if (wr == 1) PG8_BAR; }
.LBB0_1139:
	s_ashr_i32 s23, s22, 31
	s_lshl_b64 s[24:25], s[22:23], 19
	s_add_u32 s24, s46, s24
	s_addc_u32 s25, s47, s25
	s_and_b64 s[26:27], s[6:7], exec
	s_cselect_b32 s23, s25, s35
	s_cselect_b32 s31, s24, s34
	s_ashr_i32 s21, s20, 31
	s_lshl_b64 s[26:27], s[20:21], 19
	s_add_u32 s26, s33, s26
	s_addc_u32 s27, s44, s27
	s_and_b64 s[36:37], s[6:7], exec
	s_cselect_b32 s21, s27, s1
	s_cselect_b32 s91, s26, s0
	s_add_u32 s92, s0, 0x10000
	s_addc_u32 s93, s1, 0
	s_add_u32 s0, s34, 0x40080
	v_mov_b32_e32 v2, 0
	s_addc_u32 s1, s35, 0
	s_mov_b32 s94, -2
	s_and_b64 vcc, exec, s[14:15]
	s_cbranch_vccnz .Lrb_m2
	s_barrier
.Lrb_m2:
	s_add_u32 s34, s0, 0xfffc0080
	s_addc_u32 s35, s1, -1
	s_add_i32 s52, 0, 0x10000
	s_cmp_eq_u32 s94, 12
	s_cselect_b32 s37, s23, s35
	s_cselect_b32 s36, s31, s34
	s_cselect_b32 s35, s21, s93
	s_cselect_b32 s34, s91, s92
	s_add_i32 s75, 0, 0x14000
	v_add_u32_e32 v142, s52, v223
	v_add_u32_e32 v158, s75, v223
	ds_read_b128 v[130:133], v142
	v_pk_mov_b32 v[2:3], 0, 0
	v_pk_mov_b32 v[4:5], 0, 0
	v_pk_mov_b32 v[6:7], 0, 0
	v_pk_mov_b32 v[8:9], 0, 0
	ds_read_b128 v[134:137], v142 offset:1024
	v_pk_mov_b32 v[10:11], 0, 0
	v_pk_mov_b32 v[12:13], 0, 0
	v_pk_mov_b32 v[14:15], 0, 0
	v_pk_mov_b32 v[16:17], 0, 0
	ds_read_b128 v[138:141], v142 offset:2048
	v_pk_mov_b32 v[18:19], 0, 0
	v_pk_mov_b32 v[20:21], 0, 0
	v_pk_mov_b32 v[22:23], 0, 0
	v_pk_mov_b32 v[24:25], 0, 0
	ds_read_b128 v[142:145], v142 offset:3072
	v_pk_mov_b32 v[26:27], 0, 0
	v_pk_mov_b32 v[28:29], 0, 0
	v_pk_mov_b32 v[30:31], 0, 0
	v_pk_mov_b32 v[32:33], 0, 0
	ds_read_b128 v[146:149], v158
	v_pk_mov_b32 v[34:35], 0, 0
	v_pk_mov_b32 v[36:37], 0, 0
	v_pk_mov_b32 v[38:39], 0, 0
	v_pk_mov_b32 v[40:41], 0, 0
	ds_read_b128 v[150:153], v158 offset:1024
	v_pk_mov_b32 v[42:43], 0, 0
	v_pk_mov_b32 v[44:45], 0, 0
	v_pk_mov_b32 v[46:47], 0, 0
	v_pk_mov_b32 v[48:49], 0, 0
	ds_read_b128 v[154:157], v158 offset:2048
	v_pk_mov_b32 v[50:51], 0, 0
	v_pk_mov_b32 v[52:53], 0, 0
	v_pk_mov_b32 v[54:55], 0, 0
	v_pk_mov_b32 v[56:57], 0, 0
	ds_read_b128 v[158:161], v158 offset:3072
	v_pk_mov_b32 v[58:59], 0, 0
	v_pk_mov_b32 v[60:61], 0, 0
	v_pk_mov_b32 v[62:63], 0, 0
	v_pk_mov_b32 v[64:65], 0, 0
	v_lshl_add_u64 v[188:189], s[0:1], 0, v[202:203]
	s_add_i32 m0, s29, 0xc000
	ds_read_b128 v[162:165], v225
	v_pk_mov_b32 v[66:67], 0, 0
	v_pk_mov_b32 v[68:69], 0, 0
	v_pk_mov_b32 v[70:71], 0, 0
	v_pk_mov_b32 v[72:73], 0, 0
	ds_read_b128 v[166:169], v225 offset:1024
	v_pk_mov_b32 v[74:75], 0, 0
	v_pk_mov_b32 v[76:77], 0, 0
	v_pk_mov_b32 v[78:79], 0, 0
	v_pk_mov_b32 v[80:81], 0, 0
	ds_read_b128 v[170:173], v225 offset:2048
	v_pk_mov_b32 v[82:83], 0, 0
	v_pk_mov_b32 v[84:85], 0, 0
	v_pk_mov_b32 v[86:87], 0, 0
	v_pk_mov_b32 v[88:89], 0, 0
	ds_read_b128 v[174:177], v225 offset:3072
	v_pk_mov_b32 v[90:91], 0, 0
	v_pk_mov_b32 v[92:93], 0, 0
	v_pk_mov_b32 v[94:95], 0, 0
	v_pk_mov_b32 v[96:97], 0, 0
	ds_read_b128 v[178:181], v225 offset:4096
	v_pk_mov_b32 v[98:99], 0, 0
	v_pk_mov_b32 v[100:101], 0, 0
	v_pk_mov_b32 v[102:103], 0, 0
	v_pk_mov_b32 v[104:105], 0, 0
	ds_read_b128 v[182:185], v225 offset:5120
	v_pk_mov_b32 v[106:107], 0, 0
	v_pk_mov_b32 v[108:109], 0, 0
	v_pk_mov_b32 v[110:111], 0, 0
	v_pk_mov_b32 v[112:113], 0, 0
	ds_read_b128 v[206:209], v225 offset:6144
	v_pk_mov_b32 v[114:115], 0, 0
	v_pk_mov_b32 v[116:117], 0, 0
	v_pk_mov_b32 v[118:119], 0, 0
	v_pk_mov_b32 v[120:121], 0, 0
	ds_read_b128 v[210:213], v225 offset:7168
	v_pk_mov_b32 v[122:123], 0, 0
	v_pk_mov_b32 v[124:125], 0, 0
	v_pk_mov_b32 v[126:127], 0, 0
	v_pk_mov_b32 v[128:129], 0, 0
	global_load_lds_dwordx4 v[188:189], off
	v_lshl_add_u64 v[188:189], s[0:1], 0, v[204:205]
	s_add_i32 m0, s29, 0xe000
	s_nop 0
	global_load_lds_dwordx4 v[188:189], off
	s_waitcnt vmcnt(8)
	s_waitcnt lgkmcnt(0)
	s_barrier
	s_branch .Lpeel_1140

; #define PG8_STAGE(bufoff, gbase, voff) do { _Pragma("unroll") for (int _i = 0; _i < 2; ++_i) \
;         __builtin_amdgcn_global_load_lds((const unsigned*)((const char*)(gbase) + (voff)[_i]), (PG8_LAS unsigned*)(lds + (bufoff) + ldsw + _i * 8192), 16, 0, 0); } while (0)
; #define PG8_LDA(dst, b, h) do { _Pragma("unroll") for (int m = 0; m < 4; ++m) _Pragma("unroll") for (int k = 0; k < 2; ++k) dst[m][k] = *(const PG8_LAS bf16x8*)(lds + PG8_SA(b, h) + aoff + m * 2048 + k * 1024); } while (0)
; #define PG8_LDB(dst, b, h) do { _Pragma("unroll") for (int n = 0; n < 2; ++n) _Pragma("unroll") for (int k = 0; k < 2; ++k) dst[n][k] = *(const PG8_LAS bf16x8*)(lds + PG8_SB(b, h) + boff + n * 2048 + k * 1024); } while (0)
; #define PG8_WAIT_V(n) asm volatile("s_waitcnt vmcnt(" #n ")" ::: "memory")
; #define PG8_WAIT_L(n) asm volatile("s_waitcnt lgkmcnt(" #n ")" ::: "memory")
; template <class Epi, class Sched, bool ALIGN_EPI = false, bool SP2 = false, bool ABLK = false, bool BBLK = false>
; __device__ __forceinline__ void gemm_phase(PG8_LAS unsigned char* lds, const Gemm g, const Sched& S, const Epi& E) {
;     ...
;         const char* nA = has_next ? (const char*)g.A + (size_t)nxt.pm * tstepA : cA; const char* nB = has_next ? (const char*)g.Bt + (size_t)nxt.pn * tstepB : cB;
;         for (int t = 0; t < nt; t += 2) {
;             const bool last = (t == nt - 2);
;             const char* a1 = cA + (size_t)(t + 1) * kstepA;
;             const char* a2 = last ? nA : cA + (size_t)(t + 2) * kstepA; const char* b2 = last ? nB : cB + (size_t)(t + 2) * kstepB;
;             const char* a3 = a2 + kstepA; const char* b3 = b2 + kstepB;
;             if (last && has_next) S.a_ready(nxt);
;             if constexpr (SP2) {
;             PG8_LDB(B0, 0, 0); PG8_LDB(B1, 0, 1); PG8_SCHED; PG8_LDA(At, 0, 0); PG8_STAGE(PG8_SA(1, 1), a1 + hstepA, voffA);
;             PG8_WAIT_V(8); PG8_WAIT_L(0); PG8_BAR; PG8_MMA(0, 0, At, B0); PG8_MMA(0, 1, At, B1); PG8_BAR; PG8_SCHED;
;     ...
; #pragma unroll
;         for (int a = 0; a < 2; ++a)
; #pragma unroll
;             for (int b = 0; b < 2; ++b)
; #pragma unroll
;                 for (int m = 0; m < 4; ++m)
; #pragma unroll
;                     for (int n = 0; n < 2; ++n) acc[a][b][m][n] = (f32x4){0.f, 0.f, 0.f, 0.f};
;         cur = nxt; cA = nA; cB = nB; ++ui;
;         if constexpr (ALIGN_EPI) { if (wr == 1) PG8_BAR; }
.LBB0_1162:
	s_ashr_i32 s21, s20, 31
	s_lshl_b64 s[22:23], s[20:21], 18
	s_add_u32 s22, s33, s22
	s_addc_u32 s23, s36, s23
	s_and_b64 s[24:25], s[6:7], exec
	s_cselect_b32 s21, s23, s31
	s_cselect_b32 s29, s22, s30
	s_ashr_i32 s19, s18, 31
	s_lshl_b64 s[24:25], s[18:19], 18
	s_add_u32 s24, s37, s24
	s_addc_u32 s25, s44, s25
	s_and_b64 s[34:35], s[6:7], exec
	s_cselect_b32 s19, s25, s1
	s_cselect_b32 s61, s24, s0
	s_add_u32 s83, s0, 0x10000
	s_addc_u32 s84, s1, 0
	s_add_u32 s0, s30, 0x20080
	v_mov_b32_e32 v2, 0
	s_addc_u32 s1, s31, 0
	s_mov_b32 s86, -2
	s_and_b64 vcc, exec, s[12:13]
	s_cbranch_vccnz .Lrb_m3
	s_barrier
.Lrb_m3:
	s_add_u32 s30, s0, 0xfffe0080
	s_addc_u32 s31, s1, -1
	s_add_i32 s52, 0, 0x10000
	s_cmp_eq_u32 s86, 4
	s_cselect_b32 s35, s21, s31
	s_cselect_b32 s34, s29, s30
	s_cselect_b32 s31, s19, s84
	s_cselect_b32 s30, s61, s83
	s_add_i32 s75, 0, 0x14000
	v_add_u32_e32 v142, s52, v223
	v_add_u32_e32 v158, s75, v223
	ds_read_b128 v[130:133], v142
	v_pk_mov_b32 v[2:3], 0, 0
	v_pk_mov_b32 v[4:5], 0, 0
	v_pk_mov_b32 v[6:7], 0, 0
	v_pk_mov_b32 v[8:9], 0, 0
	ds_read_b128 v[134:137], v142 offset:1024
	v_pk_mov_b32 v[10:11], 0, 0
	v_pk_mov_b32 v[12:13], 0, 0
	v_pk_mov_b32 v[14:15], 0, 0
	v_pk_mov_b32 v[16:17], 0, 0
	ds_read_b128 v[138:141], v142 offset:2048
	v_pk_mov_b32 v[18:19], 0, 0
	v_pk_mov_b32 v[20:21], 0, 0
	v_pk_mov_b32 v[22:23], 0, 0
	v_pk_mov_b32 v[24:25], 0, 0
	ds_read_b128 v[142:145], v142 offset:3072
	v_pk_mov_b32 v[26:27], 0, 0
	v_pk_mov_b32 v[28:29], 0, 0
	v_pk_mov_b32 v[30:31], 0, 0
	v_pk_mov_b32 v[32:33], 0, 0
	ds_read_b128 v[146:149], v158
	v_pk_mov_b32 v[34:35], 0, 0
	v_pk_mov_b32 v[36:37], 0, 0
	v_pk_mov_b32 v[38:39], 0, 0
	v_pk_mov_b32 v[40:41], 0, 0
	ds_read_b128 v[150:153], v158 offset:1024
	v_pk_mov_b32 v[42:43], 0, 0
	v_pk_mov_b32 v[44:45], 0, 0
	v_pk_mov_b32 v[46:47], 0, 0
	v_pk_mov_b32 v[48:49], 0, 0
	ds_read_b128 v[154:157], v158 offset:2048
	v_pk_mov_b32 v[50:51], 0, 0
	v_pk_mov_b32 v[52:53], 0, 0
	v_pk_mov_b32 v[54:55], 0, 0
	v_pk_mov_b32 v[56:57], 0, 0
	ds_read_b128 v[158:161], v158 offset:3072
	v_pk_mov_b32 v[58:59], 0, 0
	v_pk_mov_b32 v[60:61], 0, 0
	v_pk_mov_b32 v[62:63], 0, 0
	v_pk_mov_b32 v[64:65], 0, 0
	v_lshl_add_u64 v[188:189], s[0:1], 0, v[202:203]
	s_add_i32 m0, s27, 0xc000
	ds_read_b128 v[162:165], v225
	v_pk_mov_b32 v[66:67], 0, 0
	v_pk_mov_b32 v[68:69], 0, 0
	v_pk_mov_b32 v[70:71], 0, 0
	v_pk_mov_b32 v[72:73], 0, 0
	ds_read_b128 v[166:169], v225 offset:1024
	v_pk_mov_b32 v[74:75], 0, 0
	v_pk_mov_b32 v[76:77], 0, 0
	v_pk_mov_b32 v[78:79], 0, 0
	v_pk_mov_b32 v[80:81], 0, 0
	ds_read_b128 v[170:173], v225 offset:2048
	v_pk_mov_b32 v[82:83], 0, 0
	v_pk_mov_b32 v[84:85], 0, 0
	v_pk_mov_b32 v[86:87], 0, 0
	v_pk_mov_b32 v[88:89], 0, 0
	ds_read_b128 v[174:177], v225 offset:3072
	v_pk_mov_b32 v[90:91], 0, 0
	v_pk_mov_b32 v[92:93], 0, 0
	v_pk_mov_b32 v[94:95], 0, 0
	v_pk_mov_b32 v[96:97], 0, 0
	ds_read_b128 v[178:181], v225 offset:4096
	v_pk_mov_b32 v[98:99], 0, 0
	v_pk_mov_b32 v[100:101], 0, 0
	v_pk_mov_b32 v[102:103], 0, 0
	v_pk_mov_b32 v[104:105], 0, 0
	ds_read_b128 v[182:185], v225 offset:5120
	v_pk_mov_b32 v[106:107], 0, 0
	v_pk_mov_b32 v[108:109], 0, 0
	v_pk_mov_b32 v[110:111], 0, 0
	v_pk_mov_b32 v[112:113], 0, 0
	ds_read_b128 v[206:209], v225 offset:6144
	v_pk_mov_b32 v[114:115], 0, 0
	v_pk_mov_b32 v[116:117], 0, 0
	v_pk_mov_b32 v[118:119], 0, 0
	v_pk_mov_b32 v[120:121], 0, 0
	ds_read_b128 v[210:213], v225 offset:7168
	v_pk_mov_b32 v[122:123], 0, 0
	v_pk_mov_b32 v[124:125], 0, 0
	v_pk_mov_b32 v[126:127], 0, 0
	v_pk_mov_b32 v[128:129], 0, 0
	global_load_lds_dwordx4 v[188:189], off
	v_lshl_add_u64 v[188:189], s[0:1], 0, v[204:205]
	s_add_i32 m0, s27, 0xe000
	s_nop 0
	global_load_lds_dwordx4 v[188:189], off
	s_waitcnt vmcnt(8)
	s_waitcnt lgkmcnt(0)
	s_barrier
	s_branch .Lpeel_1163

; #define PG8_STAGE(bufoff, gbase, voff) do { _Pragma("unroll") for (int _i = 0; _i < 2; ++_i) \
;         __builtin_amdgcn_global_load_lds((const unsigned*)((const char*)(gbase) + (voff)[_i]), (PG8_LAS unsigned*)(lds + (bufoff) + ldsw + _i * 8192), 16, 0, 0); } while (0)
; #define PG8_LDA(dst, b, h) do { _Pragma("unroll") for (int m = 0; m < 4; ++m) _Pragma("unroll") for (int k = 0; k < 2; ++k) dst[m][k] = *(const PG8_LAS bf16x8*)(lds + PG8_SA(b, h) + aoff + m * 2048 + k * 1024); } while (0)
; #define PG8_LDB(dst, b, h) do { _Pragma("unroll") for (int n = 0; n < 2; ++n) _Pragma("unroll") for (int k = 0; k < 2; ++k) dst[n][k] = *(const PG8_LAS bf16x8*)(lds + PG8_SB(b, h) + boff + n * 2048 + k * 1024); } while (0)
; #define PG8_WAIT_V(n) asm volatile("s_waitcnt vmcnt(" #n ")" ::: "memory")
; #define PG8_WAIT_L(n) asm volatile("s_waitcnt lgkmcnt(" #n ")" ::: "memory")
; template <class Epi, class Sched, bool ALIGN_EPI = false, bool SP2 = false, bool ABLK = false, bool BBLK = false>
; __device__ __forceinline__ void gemm_phase(PG8_LAS unsigned char* lds, const Gemm g, const Sched& S, const Epi& E) {
;     ...
;         const char* nA = has_next ? (const char*)g.A + (size_t)nxt.pm * tstepA : cA; const char* nB = has_next ? (const char*)g.Bt + (size_t)nxt.pn * tstepB : cB;
;         for (int t = 0; t < nt; t += 2) {
;             const bool last = (t == nt - 2);
;             const char* a1 = cA + (size_t)(t + 1) * kstepA;
;             const char* a2 = last ? nA : cA + (size_t)(t + 2) * kstepA; const char* b2 = last ? nB : cB + (size_t)(t + 2) * kstepB;
;             const char* a3 = a2 + kstepA; const char* b3 = b2 + kstepB;
;             if (last && has_next) S.a_ready(nxt);
;             if constexpr (SP2) {
;             PG8_LDB(B0, 0, 0); PG8_LDB(B1, 0, 1); PG8_SCHED; PG8_LDA(At, 0, 0); PG8_STAGE(PG8_SA(1, 1), a1 + hstepA, voffA);
;             PG8_WAIT_V(8); PG8_WAIT_L(0); PG8_BAR; PG8_MMA(0, 0, At, B0); PG8_MMA(0, 1, At, B1); PG8_BAR; PG8_SCHED;
;     ...
; #pragma unroll
;         for (int a = 0; a < 2; ++a)
; #pragma unroll
;             for (int b = 0; b < 2; ++b)
; #pragma unroll
;                 for (int m = 0; m < 4; ++m)
; #pragma unroll
;                     for (int n = 0; n < 2; ++n) acc[a][b][m][n] = (f32x4){0.f, 0.f, 0.f, 0.f};
;         cur = nxt; cA = nA; cB = nB; ++ui;
;         if constexpr (ALIGN_EPI) { if (wr == 1) PG8_BAR; }
.LBB0_1238:
	s_ashr_i32 s27, s26, 31
	s_lshl_b64 s[28:29], s[26:27], 20
	s_add_u32 s28, s50, s28
	s_addc_u32 s29, s51, s29
	s_and_b64 s[30:31], s[6:7], exec
	s_cselect_b32 s27, s29, s9
	s_cselect_b32 s35, s28, s8
	s_ashr_i32 s25, s24, 31
	s_lshl_b64 s[30:31], s[24:25], 20
	s_add_u32 s30, s53, s30
	s_addc_u32 s31, s56, s31
	s_and_b64 s[40:41], s[6:7], exec
	s_cselect_b32 s25, s31, s1
	s_cselect_b32 s37, s30, s0
	s_add_u32 s60, s0, 0x10000
	s_addc_u32 s61, s1, 0
	s_add_u32 s0, s8, 0x80080
	v_mov_b32_e32 v38, 0
	s_addc_u32 s1, s9, 0
	s_mov_b32 s92, -2
	s_and_b64 vcc, exec, s[18:19]
	s_cbranch_vccnz .Lrb_mo
	s_barrier
.Lrb_mo:
	s_add_u32 s8, s0, 0xfff80080
	s_addc_u32 s9, s1, -1
	s_add_i32 s52, 0, 0x10000
	s_cmp_eq_u32 s92, 28
	s_cselect_b32 s41, s27, s9
	s_cselect_b32 s40, s35, s8
	s_cselect_b32 s9, s25, s61
	s_cselect_b32 s8, s37, s60
	s_add_i32 s75, 0, 0x14000
	v_add_u32_e32 v142, s52, v206
	v_add_u32_e32 v158, s75, v206
	ds_read_b128 v[122:125], v142
	v_pk_mov_b32 v[2:3], 0, 0
	v_pk_mov_b32 v[4:5], 0, 0
	v_pk_mov_b32 v[6:7], 0, 0
	v_pk_mov_b32 v[8:9], 0, 0
	ds_read_b128 v[126:129], v142 offset:1024
	v_pk_mov_b32 v[10:11], 0, 0
	v_pk_mov_b32 v[12:13], 0, 0
	v_pk_mov_b32 v[14:15], 0, 0
	v_pk_mov_b32 v[16:17], 0, 0
	ds_read_b128 v[138:141], v142 offset:2048
	v_pk_mov_b32 v[18:19], 0, 0
	v_pk_mov_b32 v[20:21], 0, 0
	v_pk_mov_b32 v[22:23], 0, 0
	v_pk_mov_b32 v[24:25], 0, 0
	ds_read_b128 v[142:145], v142 offset:3072
	v_pk_mov_b32 v[26:27], 0, 0
	v_pk_mov_b32 v[28:29], 0, 0
	v_pk_mov_b32 v[30:31], 0, 0
	v_pk_mov_b32 v[32:33], 0, 0
	ds_read_b128 v[146:149], v158
	v_pk_mov_b32 v[34:35], 0, 0
	v_pk_mov_b32 v[36:37], 0, 0
	v_pk_mov_b32 v[38:39], 0, 0
	v_pk_mov_b32 v[40:41], 0, 0
	ds_read_b128 v[150:153], v158 offset:1024
	v_pk_mov_b32 v[42:43], 0, 0
	v_pk_mov_b32 v[44:45], 0, 0
	v_pk_mov_b32 v[46:47], 0, 0
	v_pk_mov_b32 v[48:49], 0, 0
	ds_read_b128 v[154:157], v158 offset:2048
	v_pk_mov_b32 v[50:51], 0, 0
	v_pk_mov_b32 v[52:53], 0, 0
	v_pk_mov_b32 v[54:55], 0, 0
	v_pk_mov_b32 v[56:57], 0, 0
	ds_read_b128 v[158:161], v158 offset:3072
	v_pk_mov_b32 v[58:59], 0, 0
	v_pk_mov_b32 v[60:61], 0, 0
	v_pk_mov_b32 v[62:63], 0, 0
	v_pk_mov_b32 v[64:65], 0, 0
	v_lshl_add_u64 v[188:189], s[0:1], 0, v[184:185]
	s_add_i32 m0, s47, 0xc000
	ds_read_b128 v[162:165], v207
	v_pk_mov_b32 v[66:67], 0, 0
	v_pk_mov_b32 v[68:69], 0, 0
	v_pk_mov_b32 v[70:71], 0, 0
	v_pk_mov_b32 v[72:73], 0, 0
	ds_read_b128 v[166:169], v207 offset:1024
	v_pk_mov_b32 v[74:75], 0, 0
	v_pk_mov_b32 v[76:77], 0, 0
	v_pk_mov_b32 v[78:79], 0, 0
	v_pk_mov_b32 v[80:81], 0, 0
	ds_read_b128 v[170:173], v207 offset:2048
	v_pk_mov_b32 v[82:83], 0, 0
	v_pk_mov_b32 v[84:85], 0, 0
	v_pk_mov_b32 v[86:87], 0, 0
	v_pk_mov_b32 v[88:89], 0, 0
	ds_read_b128 v[174:177], v207 offset:3072
	v_pk_mov_b32 v[90:91], 0, 0
	v_pk_mov_b32 v[92:93], 0, 0
	v_pk_mov_b32 v[94:95], 0, 0
	v_pk_mov_b32 v[96:97], 0, 0
	ds_read_b128 v[198:201], v207 offset:4096
	v_pk_mov_b32 v[98:99], 0, 0
	v_pk_mov_b32 v[100:101], 0, 0
	v_pk_mov_b32 v[102:103], 0, 0
	v_pk_mov_b32 v[104:105], 0, 0
	ds_read_b128 v[208:211], v207 offset:5120
	v_pk_mov_b32 v[106:107], 0, 0
	v_pk_mov_b32 v[108:109], 0, 0
	v_pk_mov_b32 v[110:111], 0, 0
	v_pk_mov_b32 v[112:113], 0, 0
	ds_read_b128 v[212:215], v207 offset:6144
	v_pk_mov_b32 v[114:115], 0, 0
	v_pk_mov_b32 v[116:117], 0, 0
	v_pk_mov_b32 v[118:119], 0, 0
	v_pk_mov_b32 v[120:121], 0, 0
	ds_read_b128 v[216:219], v207 offset:7168
	v_pk_mov_b32 v[130:131], 0, 0
	v_pk_mov_b32 v[132:133], 0, 0
	v_pk_mov_b32 v[134:135], 0, 0
	v_pk_mov_b32 v[136:137], 0, 0
	global_load_lds_dwordx4 v[188:189], off
	v_lshl_add_u64 v[188:189], s[0:1], 0, v[196:197]
	s_add_i32 m0, s47, 0xe000
	s_nop 0
	global_load_lds_dwordx4 v[188:189], off
	s_waitcnt vmcnt(8)
	s_waitcnt lgkmcnt(0)
	s_barrier
	s_branch .Lpeel_1239

; #define PG8_STAGE(bufoff, gbase, voff) do { _Pragma("unroll") for (int _i = 0; _i < 2; ++_i) \
;         __builtin_amdgcn_global_load_lds((const unsigned*)((const char*)(gbase) + (voff)[_i]), (PG8_LAS unsigned*)(lds + (bufoff) + ldsw + _i * 8192), 16, 0, 0); } while (0)
; #define PG8_LDA(dst, b, h) do { _Pragma("unroll") for (int m = 0; m < 4; ++m) _Pragma("unroll") for (int k = 0; k < 2; ++k) dst[m][k] = *(const PG8_LAS bf16x8*)(lds + PG8_SA(b, h) + aoff + m * 2048 + k * 1024); } while (0)
; #define PG8_LDB(dst, b, h) do { _Pragma("unroll") for (int n = 0; n < 2; ++n) _Pragma("unroll") for (int k = 0; k < 2; ++k) dst[n][k] = *(const PG8_LAS bf16x8*)(lds + PG8_SB(b, h) + boff + n * 2048 + k * 1024); } while (0)
; #define PG8_WAIT_V(n) asm volatile("s_waitcnt vmcnt(" #n ")" ::: "memory")
; #define PG8_WAIT_L(n) asm volatile("s_waitcnt lgkmcnt(" #n ")" ::: "memory")
; template <class Epi, class Sched, bool ALIGN_EPI = false, bool SP2 = false, bool ABLK = false, bool BBLK = false>
; __device__ __forceinline__ void gemm_phase(PG8_LAS unsigned char* lds, const Gemm g, const Sched& S, const Epi& E) {
;     ...
;         const char* nA = has_next ? (const char*)g.A + (size_t)nxt.pm * tstepA : cA; const char* nB = has_next ? (const char*)g.Bt + (size_t)nxt.pn * tstepB : cB;
;         for (int t = 0; t < nt; t += 2) {
;             const bool last = (t == nt - 2);
;             const char* a1 = cA + (size_t)(t + 1) * kstepA;
;             const char* a2 = last ? nA : cA + (size_t)(t + 2) * kstepA; const char* b2 = last ? nB : cB + (size_t)(t + 2) * kstepB;
;             const char* a3 = a2 + kstepA; const char* b3 = b2 + kstepB;
;             if (last && has_next) S.a_ready(nxt);
;             if constexpr (SP2) {
;             PG8_LDB(B0, 0, 0); PG8_LDB(B1, 0, 1); PG8_SCHED; PG8_LDA(At, 0, 0); PG8_STAGE(PG8_SA(1, 1), a1 + hstepA, voffA);
;             PG8_WAIT_V(8); PG8_WAIT_L(0); PG8_BAR; PG8_MMA(0, 0, At, B0); PG8_MMA(0, 1, At, B1); PG8_BAR; PG8_SCHED;
;     ...
; #pragma unroll
;         for (int a = 0; a < 2; ++a)
; #pragma unroll
;             for (int b = 0; b < 2; ++b)
; #pragma unroll
;                 for (int m = 0; m < 4; ++m)
; #pragma unroll
;                     for (int n = 0; n < 2; ++n) acc[a][b][m][n] = (f32x4){0.f, 0.f, 0.f, 0.f};
;         cur = nxt; cA = nA; cB = nB; ++ui;
;         if constexpr (ALIGN_EPI) { if (wr == 1) PG8_BAR; }
.LBB0_1339:
	s_ashr_i32 s19, s18, 31
	s_lshl_b64 s[20:21], s[18:19], 20
	s_add_u32 s20, s40, s20
	s_addc_u32 s21, s41, s21
	s_and_b64 s[22:23], s[6:7], exec
	s_cselect_b32 s1, s21, s27
	s_cselect_b32 s19, s20, s26
	s_ashr_i32 s15, s14, 31
	s_lshl_b64 s[22:23], s[14:15], 20
	s_add_u32 s22, s42, s22
	s_addc_u32 s23, s43, s23
	s_and_b64 s[30:31], s[6:7], exec
	s_cselect_b32 s15, s23, s29
	s_cselect_b32 s72, s22, s28
	s_add_u32 s26, s26, 0xc000
	s_addc_u32 s27, s27, 0
	s_add_u32 s73, s28, 0x10000
	v_mov_b32_e32 v2, 0
	s_addc_u32 s81, s29, 0
	s_mov_b32 s83, -2
	s_and_b64 vcc, exec, s[12:13]
	s_cbranch_vccnz .Lrb_f2a
	s_barrier
.Lrb_f2a:
	s_add_u32 s28, s26, 0x4000
	s_addc_u32 s29, s27, 0
	s_cmp_eq_u32 s83, 28
	s_cselect_b32 s34, s19, s28
	s_cselect_b32 s35, s1, s29
	s_cselect_b32 s30, s72, s73
	s_cselect_b32 s31, s15, s81
	s_add_u32 s28, s34, 0x8000
	s_addc_u32 s29, s35, 0
	s_add_i32 s52, 0, 0x10000
	v_add_u32_e32 v142, s52, v145
	s_add_i32 s75, 0, 0x14000
	ds_read_b128 v[148:151], v142
	v_pk_mov_b32 v[2:3], 0, 0
	v_pk_mov_b32 v[4:5], 0, 0
	v_pk_mov_b32 v[6:7], 0, 0
	v_pk_mov_b32 v[8:9], 0, 0
	ds_read_b128 v[152:155], v142 offset:1024
	v_pk_mov_b32 v[10:11], 0, 0
	v_pk_mov_b32 v[12:13], 0, 0
	v_pk_mov_b32 v[14:15], 0, 0
	v_pk_mov_b32 v[16:17], 0, 0
	ds_read_b128 v[156:159], v142 offset:2048
	v_pk_mov_b32 v[18:19], 0, 0
	v_pk_mov_b32 v[20:21], 0, 0
	v_pk_mov_b32 v[22:23], 0, 0
	v_pk_mov_b32 v[24:25], 0, 0
	ds_read_b128 v[160:163], v142 offset:3072
	v_pk_mov_b32 v[26:27], 0, 0
	v_pk_mov_b32 v[28:29], 0, 0
	v_pk_mov_b32 v[30:31], 0, 0
	v_pk_mov_b32 v[32:33], 0, 0
	v_add_u32_e32 v142, s75, v145
	ds_read_b128 v[164:167], v142
	v_pk_mov_b32 v[34:35], 0, 0
	v_pk_mov_b32 v[36:37], 0, 0
	v_pk_mov_b32 v[38:39], 0, 0
	v_pk_mov_b32 v[40:41], 0, 0
	ds_read_b128 v[168:171], v142 offset:1024
	v_pk_mov_b32 v[42:43], 0, 0
	v_pk_mov_b32 v[44:45], 0, 0
	v_pk_mov_b32 v[46:47], 0, 0
	v_pk_mov_b32 v[48:49], 0, 0
	ds_read_b128 v[172:175], v142 offset:2048
	v_pk_mov_b32 v[50:51], 0, 0
	v_pk_mov_b32 v[52:53], 0, 0
	v_pk_mov_b32 v[54:55], 0, 0
	v_pk_mov_b32 v[56:57], 0, 0
	ds_read_b128 v[176:179], v142 offset:3072
	v_pk_mov_b32 v[58:59], 0, 0
	v_pk_mov_b32 v[60:61], 0, 0
	v_pk_mov_b32 v[62:63], 0, 0
	v_pk_mov_b32 v[64:65], 0, 0
	v_lshl_add_u64 v[142:143], s[26:27], 0, v[138:139]
	s_add_i32 m0, s25, 0xc000
	ds_read_b128 v[180:183], v146
	v_pk_mov_b32 v[66:67], 0, 0
	v_pk_mov_b32 v[68:69], 0, 0
	v_pk_mov_b32 v[70:71], 0, 0
	v_pk_mov_b32 v[72:73], 0, 0
	ds_read_b128 v[196:199], v146 offset:1024
	v_pk_mov_b32 v[74:75], 0, 0
	v_pk_mov_b32 v[76:77], 0, 0
	v_pk_mov_b32 v[78:79], 0, 0
	v_pk_mov_b32 v[80:81], 0, 0
	ds_read_b128 v[200:203], v146 offset:2048
	v_pk_mov_b32 v[82:83], 0, 0
	v_pk_mov_b32 v[84:85], 0, 0
	v_pk_mov_b32 v[86:87], 0, 0
	v_pk_mov_b32 v[88:89], 0, 0
	ds_read_b128 v[204:207], v146 offset:3072
	v_pk_mov_b32 v[90:91], 0, 0
	v_pk_mov_b32 v[92:93], 0, 0
	v_pk_mov_b32 v[94:95], 0, 0
	v_pk_mov_b32 v[96:97], 0, 0
	ds_read_b128 v[208:211], v146 offset:4096
	v_pk_mov_b32 v[98:99], 0, 0
	v_pk_mov_b32 v[100:101], 0, 0
	v_pk_mov_b32 v[102:103], 0, 0
	v_pk_mov_b32 v[104:105], 0, 0
	ds_read_b128 v[212:215], v146 offset:5120
	v_pk_mov_b32 v[106:107], 0, 0
	v_pk_mov_b32 v[108:109], 0, 0
	v_pk_mov_b32 v[110:111], 0, 0
	v_pk_mov_b32 v[112:113], 0, 0
	ds_read_b128 v[216:219], v146 offset:6144
	v_pk_mov_b32 v[114:115], 0, 0
	v_pk_mov_b32 v[116:117], 0, 0
	v_pk_mov_b32 v[118:119], 0, 0
	v_pk_mov_b32 v[120:121], 0, 0
	ds_read_b128 v[220:223], v146 offset:7168
	v_pk_mov_b32 v[122:123], 0, 0
	v_pk_mov_b32 v[124:125], 0, 0
	v_pk_mov_b32 v[126:127], 0, 0
	v_pk_mov_b32 v[128:129], 0, 0
	global_load_lds_dwordx4 v[142:143], off
	v_lshl_add_u64 v[142:143], s[26:27], 0, v[140:141]
	s_add_i32 m0, s25, 0xe000
	s_nop 0
	global_load_lds_dwordx4 v[142:143], off
	s_waitcnt vmcnt(8)
	s_waitcnt lgkmcnt(0)
	s_barrier
	s_branch .Lpeel_1340

; #define PG8_STAGE(bufoff, gbase, voff) do { _Pragma("unroll") for (int _i = 0; _i < 2; ++_i) \
;         __builtin_amdgcn_global_load_lds((const unsigned*)((const char*)(gbase) + (voff)[_i]), (PG8_LAS unsigned*)(lds + (bufoff) + ldsw + _i * 8192), 16, 0, 0); } while (0)
; #define PG8_LDA(dst, b, h) do { _Pragma("unroll") for (int m = 0; m < 4; ++m) _Pragma("unroll") for (int k = 0; k < 2; ++k) dst[m][k] = *(const PG8_LAS bf16x8*)(lds + PG8_SA(b, h) + aoff + m * 2048 + k * 1024); } while (0)
; #define PG8_LDB(dst, b, h) do { _Pragma("unroll") for (int n = 0; n < 2; ++n) _Pragma("unroll") for (int k = 0; k < 2; ++k) dst[n][k] = *(const PG8_LAS bf16x8*)(lds + PG8_SB(b, h) + boff + n * 2048 + k * 1024); } while (0)
; #define PG8_WAIT_V(n) asm volatile("s_waitcnt vmcnt(" #n ")" ::: "memory")
; #define PG8_WAIT_L(n) asm volatile("s_waitcnt lgkmcnt(" #n ")" ::: "memory")
; template <class Epi, class Sched, bool ALIGN_EPI = false, bool SP2 = false, bool ABLK = false, bool BBLK = false>
; __device__ __forceinline__ void gemm_phase(PG8_LAS unsigned char* lds, const Gemm g, const Sched& S, const Epi& E) {
;     ...
;         const char* nA = has_next ? (const char*)g.A + (size_t)nxt.pm * tstepA : cA; const char* nB = has_next ? (const char*)g.Bt + (size_t)nxt.pn * tstepB : cB;
;         for (int t = 0; t < nt; t += 2) {
;             const bool last = (t == nt - 2);
;             const char* a1 = cA + (size_t)(t + 1) * kstepA;
;             const char* a2 = last ? nA : cA + (size_t)(t + 2) * kstepA; const char* b2 = last ? nB : cB + (size_t)(t + 2) * kstepB;
;             const char* a3 = a2 + kstepA; const char* b3 = b2 + kstepB;
;             if (last && has_next) S.a_ready(nxt);
;             if constexpr (SP2) {
;             PG8_LDB(B0, 0, 0); PG8_LDB(B1, 0, 1); PG8_SCHED; PG8_LDA(At, 0, 0); PG8_STAGE(PG8_SA(1, 1), a1 + hstepA, voffA);
;             PG8_WAIT_V(8); PG8_WAIT_L(0); PG8_BAR; PG8_MMA(0, 0, At, B0); PG8_MMA(0, 1, At, B1); PG8_BAR; PG8_SCHED;
;     ...
; #pragma unroll
;         for (int a = 0; a < 2; ++a)
; #pragma unroll
;             for (int b = 0; b < 2; ++b)
; #pragma unroll
;                 for (int m = 0; m < 4; ++m)
; #pragma unroll
;                     for (int n = 0; n < 2; ++n) acc[a][b][m][n] = (f32x4){0.f, 0.f, 0.f, 0.f};
;         cur = nxt; cA = nA; cB = nB; ++ui;
;         if constexpr (ALIGN_EPI) { if (wr == 1) PG8_BAR; }
.LBB0_1419:
	s_add_u32 s0, s0, 0xc000
	s_addc_u32 s1, s1, 0
	s_add_u32 s23, s26, 0x10000
	v_mov_b32_e32 v2, 0
	s_addc_u32 s25, s27, 0
	s_mov_b32 s73, -2
	s_and_b64 vcc, exec, s[14:15]
	s_cbranch_vccnz .Lrb_f2b0
	s_barrier
.Lrb_f2b0:
	s_add_u32 s8, s0, 0x4000
	s_addc_u32 s9, s1, 0
	s_cmpk_eq_i32 s73, 0x54
	s_cselect_b32 s28, s18, s8
	s_cselect_b32 s29, s19, s9
	s_cselect_b32 s26, s20, s23
	s_cselect_b32 s27, s21, s25
	s_add_u32 s8, s28, 0x8000
	s_addc_u32 s9, s29, 0
	s_add_i32 s52, 0, 0x10000
	s_add_i32 s75, 0, 0x14000
	v_add_u32_e32 v142, s52, v180
	v_add_u32_e32 v168, s75, v180
	ds_read_b128 v[130:133], v142
	v_pk_mov_b32 v[2:3], 0, 0
	v_pk_mov_b32 v[4:5], 0, 0
	v_pk_mov_b32 v[6:7], 0, 0
	v_pk_mov_b32 v[8:9], 0, 0
	ds_read_b128 v[134:137], v142 offset:1024
	v_pk_mov_b32 v[10:11], 0, 0
	v_pk_mov_b32 v[12:13], 0, 0
	v_pk_mov_b32 v[14:15], 0, 0
	v_pk_mov_b32 v[16:17], 0, 0
	ds_read_b128 v[138:141], v142 offset:2048
	v_pk_mov_b32 v[18:19], 0, 0
	v_pk_mov_b32 v[20:21], 0, 0
	v_pk_mov_b32 v[22:23], 0, 0
	v_pk_mov_b32 v[24:25], 0, 0
	ds_read_b128 v[142:145], v142 offset:3072
	v_pk_mov_b32 v[26:27], 0, 0
	v_pk_mov_b32 v[28:29], 0, 0
	v_pk_mov_b32 v[30:31], 0, 0
	v_pk_mov_b32 v[32:33], 0, 0
	ds_read_b128 v[156:159], v168
	v_pk_mov_b32 v[34:35], 0, 0
	v_pk_mov_b32 v[36:37], 0, 0
	v_pk_mov_b32 v[38:39], 0, 0
	v_pk_mov_b32 v[40:41], 0, 0
	ds_read_b128 v[160:163], v168 offset:1024
	v_pk_mov_b32 v[42:43], 0, 0
	v_pk_mov_b32 v[44:45], 0, 0
	v_pk_mov_b32 v[46:47], 0, 0
	v_pk_mov_b32 v[48:49], 0, 0
	ds_read_b128 v[164:167], v168 offset:2048
	v_pk_mov_b32 v[50:51], 0, 0
	v_pk_mov_b32 v[52:53], 0, 0
	v_pk_mov_b32 v[54:55], 0, 0
	v_pk_mov_b32 v[56:57], 0, 0
	ds_read_b128 v[168:171], v168 offset:3072
	v_pk_mov_b32 v[58:59], 0, 0
	v_pk_mov_b32 v[60:61], 0, 0
	v_pk_mov_b32 v[62:63], 0, 0
	v_pk_mov_b32 v[64:65], 0, 0
	v_lshl_add_u64 v[176:177], s[0:1], 0, v[152:153]
	s_add_i32 m0, s3, 0xc000
	ds_read_b128 v[172:175], v181
	v_pk_mov_b32 v[66:67], 0, 0
	v_pk_mov_b32 v[68:69], 0, 0
	v_pk_mov_b32 v[70:71], 0, 0
	v_pk_mov_b32 v[72:73], 0, 0
	ds_read_b128 v[182:185], v181 offset:1024
	v_pk_mov_b32 v[74:75], 0, 0
	v_pk_mov_b32 v[76:77], 0, 0
	v_pk_mov_b32 v[78:79], 0, 0
	v_pk_mov_b32 v[80:81], 0, 0
	ds_read_b128 v[196:199], v181 offset:2048
	v_pk_mov_b32 v[82:83], 0, 0
	v_pk_mov_b32 v[84:85], 0, 0
	v_pk_mov_b32 v[86:87], 0, 0
	v_pk_mov_b32 v[88:89], 0, 0
	ds_read_b128 v[200:203], v181 offset:3072
	v_pk_mov_b32 v[90:91], 0, 0
	v_pk_mov_b32 v[92:93], 0, 0
	v_pk_mov_b32 v[94:95], 0, 0
	v_pk_mov_b32 v[96:97], 0, 0
	ds_read_b128 v[204:207], v181 offset:4096
	v_pk_mov_b32 v[98:99], 0, 0
	v_pk_mov_b32 v[100:101], 0, 0
	v_pk_mov_b32 v[102:103], 0, 0
	v_pk_mov_b32 v[104:105], 0, 0
	ds_read_b128 v[208:211], v181 offset:5120
	v_pk_mov_b32 v[106:107], 0, 0
	v_pk_mov_b32 v[108:109], 0, 0
	v_pk_mov_b32 v[110:111], 0, 0
	v_pk_mov_b32 v[112:113], 0, 0
	ds_read_b128 v[212:215], v181 offset:6144
	v_pk_mov_b32 v[114:115], 0, 0
	v_pk_mov_b32 v[116:117], 0, 0
	v_pk_mov_b32 v[118:119], 0, 0
	v_pk_mov_b32 v[120:121], 0, 0
	ds_read_b128 v[216:219], v181 offset:7168
	v_pk_mov_b32 v[122:123], 0, 0
	v_pk_mov_b32 v[124:125], 0, 0
	v_pk_mov_b32 v[126:127], 0, 0
	v_pk_mov_b32 v[128:129], 0, 0
	global_load_lds_dwordx4 v[176:177], off
	v_lshl_add_u64 v[176:177], s[0:1], 0, v[154:155]
	s_add_i32 m0, s3, 0xe000
	s_nop 0
	global_load_lds_dwordx4 v[176:177], off
	s_waitcnt vmcnt(8)
	s_waitcnt lgkmcnt(0)
	s_barrier
	s_branch .Lpeel_1420

; #define PG8_STAGE(bufoff, gbase, voff) do { _Pragma("unroll") for (int _i = 0; _i < 2; ++_i) \
;         __builtin_amdgcn_global_load_lds((const unsigned*)((const char*)(gbase) + (voff)[_i]), (PG8_LAS unsigned*)(lds + (bufoff) + ldsw + _i * 8192), 16, 0, 0); } while (0)
; #define PG8_LDA(dst, b, h) do { _Pragma("unroll") for (int m = 0; m < 4; ++m) _Pragma("unroll") for (int k = 0; k < 2; ++k) dst[m][k] = *(const PG8_LAS bf16x8*)(lds + PG8_SA(b, h) + aoff + m * 2048 + k * 1024); } while (0)
; #define PG8_LDB(dst, b, h) do { _Pragma("unroll") for (int n = 0; n < 2; ++n) _Pragma("unroll") for (int k = 0; k < 2; ++k) dst[n][k] = *(const PG8_LAS bf16x8*)(lds + PG8_SB(b, h) + boff + n * 2048 + k * 1024); } while (0)
; #define PG8_WAIT_V(n) asm volatile("s_waitcnt vmcnt(" #n ")" ::: "memory")
; #define PG8_WAIT_L(n) asm volatile("s_waitcnt lgkmcnt(" #n ")" ::: "memory")
; template <class Epi, class Sched, bool ALIGN_EPI = false, bool SP2 = false, bool ABLK = false, bool BBLK = false>
; __device__ __forceinline__ void gemm_phase(PG8_LAS unsigned char* lds, const Gemm g, const Sched& S, const Epi& E) {
;     ...
;         const char* nA = has_next ? (const char*)g.A + (size_t)nxt.pm * tstepA : cA; const char* nB = has_next ? (const char*)g.Bt + (size_t)nxt.pn * tstepB : cB;
;         for (int t = 0; t < nt; t += 2) {
;             const bool last = (t == nt - 2);
;             const char* a1 = cA + (size_t)(t + 1) * kstepA;
;             const char* a2 = last ? nA : cA + (size_t)(t + 2) * kstepA; const char* b2 = last ? nB : cB + (size_t)(t + 2) * kstepB;
;             const char* a3 = a2 + kstepA; const char* b3 = b2 + kstepB;
;             if (last && has_next) S.a_ready(nxt);
;             if constexpr (SP2) {
;             PG8_LDB(B0, 0, 0); PG8_LDB(B1, 0, 1); PG8_SCHED; PG8_LDA(At, 0, 0); PG8_STAGE(PG8_SA(1, 1), a1 + hstepA, voffA);
;             PG8_WAIT_V(8); PG8_WAIT_L(0); PG8_BAR; PG8_MMA(0, 0, At, B0); PG8_MMA(0, 1, At, B1); PG8_BAR; PG8_SCHED;
;     ...
; #pragma unroll
;         for (int a = 0; a < 2; ++a)
; #pragma unroll
;             for (int b = 0; b < 2; ++b)
; #pragma unroll
;                 for (int m = 0; m < 4; ++m)
; #pragma unroll
;                     for (int n = 0; n < 2; ++n) acc[a][b][m][n] = (f32x4){0.f, 0.f, 0.f, 0.f};
;         cur = nxt; cA = nA; cB = nB; ++ui;
;         if constexpr (ALIGN_EPI) { if (wr == 1) PG8_BAR; }
.LBB0_1482:
	s_add_u32 s0, s0, 0xc000
	s_addc_u32 s1, s1, 0
	s_add_u32 s31, s36, 0x10000
	v_mov_b32_e32 v2, 0
	s_addc_u32 s33, s37, 0
	s_mov_b32 s35, -2
	s_and_b64 vcc, exec, s[20:21]
	s_cbranch_vccnz .Lrb_f2b1
	s_barrier
.Lrb_f2b1:
	s_add_u32 s8, s0, 0x4000
	s_addc_u32 s9, s1, 0
	s_cmpk_eq_i32 s35, 0x54
	s_cselect_b32 s40, s26, s8
	s_cselect_b32 s41, s27, s9
	s_cselect_b32 s36, s28, s31
	s_cselect_b32 s37, s29, s33
	s_add_u32 s8, s40, 0x8000
	s_addc_u32 s9, s41, 0
	s_add_i32 s44, 0, 0x10000
	s_add_i32 s52, 0, 0x14000
	v_add_u32_e32 v142, s44, v206
	v_add_u32_e32 v158, s52, v206
	ds_read_b128 v[130:133], v142
	v_pk_mov_b32 v[2:3], 0, 0
	v_pk_mov_b32 v[4:5], 0, 0
	v_pk_mov_b32 v[6:7], 0, 0
	v_pk_mov_b32 v[8:9], 0, 0
	ds_read_b128 v[134:137], v142 offset:1024
	v_pk_mov_b32 v[10:11], 0, 0
	v_pk_mov_b32 v[12:13], 0, 0
	v_pk_mov_b32 v[14:15], 0, 0
	v_pk_mov_b32 v[16:17], 0, 0
	ds_read_b128 v[138:141], v142 offset:2048
	v_pk_mov_b32 v[18:19], 0, 0
	v_pk_mov_b32 v[20:21], 0, 0
	v_pk_mov_b32 v[22:23], 0, 0
	v_pk_mov_b32 v[24:25], 0, 0
	ds_read_b128 v[142:145], v142 offset:3072
	v_pk_mov_b32 v[26:27], 0, 0
	v_pk_mov_b32 v[28:29], 0, 0
	v_pk_mov_b32 v[30:31], 0, 0
	v_pk_mov_b32 v[32:33], 0, 0
	ds_read_b128 v[146:149], v158
	v_pk_mov_b32 v[34:35], 0, 0
	v_pk_mov_b32 v[36:37], 0, 0
	v_pk_mov_b32 v[38:39], 0, 0
	v_pk_mov_b32 v[40:41], 0, 0
	ds_read_b128 v[150:153], v158 offset:1024
	v_pk_mov_b32 v[42:43], 0, 0
	v_pk_mov_b32 v[44:45], 0, 0
	v_pk_mov_b32 v[46:47], 0, 0
	v_pk_mov_b32 v[48:49], 0, 0
	ds_read_b128 v[154:157], v158 offset:2048
	v_pk_mov_b32 v[50:51], 0, 0
	v_pk_mov_b32 v[52:53], 0, 0
	v_pk_mov_b32 v[54:55], 0, 0
	v_pk_mov_b32 v[56:57], 0, 0
	ds_read_b128 v[158:161], v158 offset:3072
	v_pk_mov_b32 v[58:59], 0, 0
	v_pk_mov_b32 v[60:61], 0, 0
	v_pk_mov_b32 v[62:63], 0, 0
	v_pk_mov_b32 v[64:65], 0, 0
	v_lshl_add_u64 v[188:189], s[0:1], 0, v[184:185]
	s_add_i32 m0, s68, 0xc000
	ds_read_b128 v[162:165], v207
	v_pk_mov_b32 v[66:67], 0, 0
	v_pk_mov_b32 v[68:69], 0, 0
	v_pk_mov_b32 v[70:71], 0, 0
	v_pk_mov_b32 v[72:73], 0, 0
	ds_read_b128 v[166:169], v207 offset:1024
	v_pk_mov_b32 v[74:75], 0, 0
	v_pk_mov_b32 v[76:77], 0, 0
	v_pk_mov_b32 v[78:79], 0, 0
	v_pk_mov_b32 v[80:81], 0, 0
	ds_read_b128 v[170:173], v207 offset:2048
	v_pk_mov_b32 v[82:83], 0, 0
	v_pk_mov_b32 v[84:85], 0, 0
	v_pk_mov_b32 v[86:87], 0, 0
	v_pk_mov_b32 v[88:89], 0, 0
	ds_read_b128 v[174:177], v207 offset:3072
	v_pk_mov_b32 v[90:91], 0, 0
	v_pk_mov_b32 v[92:93], 0, 0
	v_pk_mov_b32 v[94:95], 0, 0
	v_pk_mov_b32 v[96:97], 0, 0
	ds_read_b128 v[198:201], v207 offset:4096
	v_pk_mov_b32 v[98:99], 0, 0
	v_pk_mov_b32 v[100:101], 0, 0
	v_pk_mov_b32 v[102:103], 0, 0
	v_pk_mov_b32 v[104:105], 0, 0
	ds_read_b128 v[208:211], v207 offset:5120
	v_pk_mov_b32 v[106:107], 0, 0
	v_pk_mov_b32 v[108:109], 0, 0
	v_pk_mov_b32 v[110:111], 0, 0
	v_pk_mov_b32 v[112:113], 0, 0
	ds_read_b128 v[212:215], v207 offset:6144
	v_pk_mov_b32 v[114:115], 0, 0
	v_pk_mov_b32 v[116:117], 0, 0
	v_pk_mov_b32 v[118:119], 0, 0
	v_pk_mov_b32 v[120:121], 0, 0
	ds_read_b128 v[216:219], v207 offset:7168
	v_pk_mov_b32 v[122:123], 0, 0
	v_pk_mov_b32 v[124:125], 0, 0
	v_pk_mov_b32 v[126:127], 0, 0
	v_pk_mov_b32 v[128:129], 0, 0
	global_load_lds_dwordx4 v[188:189], off
	v_lshl_add_u64 v[188:189], s[0:1], 0, v[196:197]
	s_add_i32 m0, s68, 0xe000
	s_nop 0
	global_load_lds_dwordx4 v[188:189], off
	s_waitcnt vmcnt(8)
	s_waitcnt lgkmcnt(0)
	s_barrier
	s_branch .Lpeel_1483
